# cross-attention: V fragments of the last two P.V steps read 8 ahead into idle registers (was 1 ahead)
# baseline (speedup 1.0000x reference)
; __device__ __forceinline__ void xattn_unit(const Args& a, LAS unsigned char* lds, int b, int h, int qb, int tid, int wave, int lane) {
;     constexpr int KS = 264, VS = 72, STG = 36864;
;     const GAS bf16* QX = (const GAS bf16*)(a.ws + WS_QX); const GAS bf16* KX = (const GAS bf16*)(a.ws + WS_KX); const GAS bf16* VTX = (const GAS bf16*)(a.ws + WS_VTX); GAS bf16* XO = (GAS bf16*)(a.ws + WS_XO);
;     const int fr = lane & 15, fq = lane >> 4; const size_t qrow = (size_t)b * SEQ + qb * 128 + 16 * wave + fr;
;     bf16x8 qf[8];
; #pragma unroll
;     for (int kk = 0; kk < 8; ++kk) qf[kk] = *(const GAS bf16x8*)(QX + qrow * DM + h * 256 + 32 * kk + 8 * fq);
;     u32x4 rr[2][4];
;     const unsigned vok = (unsigned)((tid >> 5) * DM + 8 * (tid & 31)) * 2u, vov = (unsigned)((tid >> 3) * MEMR + 8 * (tid & 7)) * 2u;
;     const GAS char* kxb = (const GAS char*)KX + ((size_t)b * 256 * DM + h * 256) * 2; const GAS char* vxb = (const GAS char*)VTX + ((size_t)h * 256 * MEMR + b * 256) * 2;
;     auto gload = [&](int j) {
;         if (j < 4) { const GAS char* p_ = kxb + (size_t)j * (64 * DM * 2);
; #pragma unroll
;             for (int i = 0; i < 4; ++i) rr[j & 1][i] = *(const GAS u32x4*)(p_ + (size_t)(vok + (unsigned)(i * 16 * DM * 2)));
;         } else { const GAS char* p_ = vxb + (size_t)(j - 4) * 128;
; #pragma unroll
;             for (int i = 0; i < 4; ++i) rr[j & 1][i] = *(const GAS u32x4*)(p_ + (size_t)(vov + (unsigned)(i * 64 * MEMR * 2)));
;         }
;     };
;     auto lstore = [&](int j) {
;         LAS bf16* base = (LAS bf16*)(lds + (j & 1) * STG);
;         if (j < 4) {
; #pragma unroll
;             for (int i = 0; i < 4; ++i) { const int id = tid + 512 * i; *(LAS u32x4*)(base + (id >> 5) * KS + 8 * (id & 31)) = rr[j & 1][i]; }
;         } else {
; #pragma unroll
;             for (int i = 0; i < 4; ++i) { const int id = tid + 512 * i; *(LAS u32x4*)(base + (id >> 3) * VS + 8 * (id & 7)) = rr[j & 1][i]; }
;         }
;     };
;     f32x4 S[16]; bf16x8 pf[8]; f32x4 O[16]; float l = 0.f;
; #pragma unroll
;     for (int i = 0; i < 16; ++i) { S[i] = (f32x4){0.f, 0.f, 0.f, 0.f}; O[i] = (f32x4){0.f, 0.f, 0.f, 0.f}; }
;     gload(0); gload(1); lstore(0); __syncthreads();
; #pragma unroll
;     for (int j = 0; j < 8; ++j) {
;         if (j < 6) gload(j + 2);
;         const LAS bf16* base = (const LAS bf16*)(lds + (j & 1) * STG);
;         if (j < 4) {
.LBB0_1518:
	s_ashr_i32 s0, s10, 4
	s_and_b32 s6, s17, 0x780
	s_add_i32 s7, s0, s12
	v_mov_b32_e32 v200, v252
	s_and_b32 s23, s0, 3
	s_add_i32 s0, s6, s70
	s_ashr_i32 s6, s7, 2
	s_ashr_i32 s7, s6, 31
	v_lshlrev_b32_e32 v192, 4, v200
	v_add_u32_e32 v216, 0x200, v200
	v_lshlrev_b32_e32 v2, 6, v200
	v_and_b32_e32 v4, 0x1f0, v192
	v_ashrrev_i32_e32 v5, 5, v216
	s_lshl_b64 s[8:9], s[6:7], 11
	v_and_b32_e32 v213, 15, v200
	v_and_or_b32 v193, v2, s18, v4
	v_mul_lo_u32 v2, v5, s20
	s_add_u32 s0, s8, s0
	v_add3_u32 v212, 0, v2, v4
	s_addc_u32 s24, s9, 0
	v_or_b32_e32 v2, s0, v213
	s_lshl_b32 s0, s23, 9
	s_lshl_b64 s[8:9], s[6:7], 19
	v_ashrrev_i32_e32 v3, 5, v200
	v_add_u32_e32 v217, 0x400, v200
	s_add_u32 s8, s13, s8
	v_mul_lo_u32 v3, v3, s20
	v_ashrrev_i32_e32 v6, 5, v217
	s_addc_u32 s9, s14, s9
	s_lshl_b32 s6, s6, 8
	v_add3_u32 v211, 0, v3, v4
	v_mul_lo_u32 v3, v6, s20
	s_lshl_b32 s7, s23, 20
	s_ashr_i32 s23, s6, 31
	v_add3_u32 v224, 0, v3, v4
	v_mov_b32_e32 v3, s24
	s_add_u32 s6, s6, s7
	v_lshlrev_b64 v[202:203], 11, v[2:3]
	s_addc_u32 s7, s23, 0
	v_add_u32_e32 v218, 0x600, v200
	v_lshl_add_u64 v[2:3], s[2:3], 0, v[202:203]
	s_lshl_b64 s[6:7], s[6:7], 1
	v_mov_b32_e32 v1, v201
	v_and_b32_e32 v214, 63, v200
	v_and_b32_e32 v0, 48, v200
	v_ashrrev_i32_e32 v7, 5, v218
	v_lshl_add_u64 v[2:3], v[2:3], 0, s[0:1]
	s_add_u32 s8, s8, s0
	v_add_u32_e32 v8, 0, v0
	v_or_b32_e32 v215, 48, v214
	v_mul_lo_u32 v5, v7, s20
	v_lshl_add_u64 v[12:13], v[2:3], 0, v[0:1]
	s_addc_u32 s9, s9, 0
	v_mad_u32_u24 v210, v213, s20, v8
	v_mad_u32_u24 v209, v215, s20, v8
	v_add_u32_e32 v194, 0x8000, v193
	v_add_u32_e32 v195, 0x10000, v193
	v_add_u32_e32 v196, 0x18000, v193
	v_add3_u32 v225, 0, v5, v4
	global_load_dwordx4 v[156:159], v[12:13], off
	global_load_dwordx4 v[120:123], v[12:13], off offset:64
	global_load_dwordx4 v[112:115], v[12:13], off offset:128
	global_load_dwordx4 v[104:107], v[12:13], off offset:192
	global_load_dwordx4 v[28:31], v[12:13], off offset:256
	global_load_dwordx4 v[8:11], v[12:13], off offset:320
	global_load_dwordx4 v[4:7], v[12:13], off offset:384
	global_load_dwordx4 v[0:3], v[12:13], off offset:448
	s_nop 0
	global_load_dwordx4 v[12:15], v193, s[8:9]
	global_load_dwordx4 v[16:19], v194, s[8:9]
	global_load_dwordx4 v[20:23], v195, s[8:9]
	global_load_dwordx4 v[24:27], v196, s[8:9]
	s_add_u32 s6, s15, s6
	s_addc_u32 s7, s16, s7
	s_add_u32 s24, s8, 0x20000
	s_addc_u32 s25, s9, 0
	global_load_dwordx4 v[32:35], v193, s[24:25]
	global_load_dwordx4 v[36:39], v194, s[24:25]
	global_load_dwordx4 v[40:43], v195, s[24:25]
	global_load_dwordx4 v[44:47], v196, s[24:25]
	s_add_u32 s24, s8, 0x40000
	s_addc_u32 s25, s9, 0
	s_add_u32 s8, s8, 0x60000
	s_addc_u32 s9, s9, 0
	v_and_b32_e32 v219, 0x70, v192
	v_lshrrev_b32_e32 v216, 3, v216
	v_cmp_lt_i32_e32 vcc, v227, v226
	s_add_i32 s10, s10, 1
	s_addk_i32 s17, 0x80
	s_cmp_ge_i32 s10, s11
	s_waitcnt vmcnt(0)
	ds_write_b128 v211, v[12:15]
	ds_write_b128 v212, v[16:19]
	ds_write_b128 v224, v[20:23]
	ds_write_b128 v225, v[24:27]
	s_waitcnt lgkmcnt(0)
	s_barrier
	global_load_dwordx4 v[12:15], v193, s[24:25]
	global_load_dwordx4 v[16:19], v194, s[24:25]
	global_load_dwordx4 v[20:23], v195, s[24:25]
	global_load_dwordx4 v[24:27], v196, s[24:25]
	ds_read_b128 v[48:51], v210
	ds_read_b128 v[52:55], v210 offset:64
	ds_read_b128 v[56:59], v210 offset:128
	ds_read_b128 v[60:63], v210 offset:192
	ds_read_b128 v[64:67], v210 offset:256
	ds_read_b128 v[68:71], v210 offset:320
	ds_read_b128 v[72:75], v210 offset:384
	ds_read_b128 v[76:79], v210 offset:448
	ds_read_b128 v[80:83], v210 offset:8448
	ds_read_b128 v[84:87], v210 offset:8512
	ds_read_b128 v[88:91], v210 offset:8576
	ds_read_b128 v[92:95], v210 offset:8640
	ds_read_b128 v[96:99], v210 offset:8704
	ds_read_b128 v[100:103], v210 offset:8768
	ds_read_b128 v[108:111], v210 offset:8832
	ds_read_b128 v[116:119], v210 offset:8896
	ds_read_b128 v[124:127], v210 offset:16896
	ds_read_b128 v[128:131], v210 offset:16960
	s_waitcnt lgkmcnt(14)
	v_mfma_f32_16x16x32_bf16 v[48:51], v[48:51], v[156:159], 0
	ds_read_b128 v[132:135], v210 offset:17024
	ds_read_b128 v[136:139], v210 offset:17088
	ds_read_b128 v[140:143], v209
	ds_read_b128 v[144:147], v210 offset:17152
	ds_read_b128 v[148:151], v210 offset:17216
	ds_read_b128 v[152:155], v210 offset:17280
	ds_read_b128 v[160:163], v210 offset:17344
	ds_read_b128 v[164:167], v209 offset:64
	ds_read_b128 v[168:171], v209 offset:128
	s_waitcnt lgkmcnt(14)
	v_mfma_f32_16x16x32_bf16 v[80:83], v[80:83], v[156:159], 0
	ds_read_b128 v[172:175], v209 offset:192
	ds_read_b128 v[176:179], v209 offset:256
	ds_read_b128 v[180:183], v209 offset:320
	s_waitcnt lgkmcnt(13)
	v_mfma_f32_16x16x32_bf16 v[124:127], v[124:127], v[156:159], 0
	v_mfma_f32_16x16x32_bf16 v[48:51], v[52:55], v[120:123], v[48:51]
	ds_read_b128 v[52:55], v209 offset:384
	ds_read_b128 v[184:187], v209 offset:448
	ds_write_b128 v211, v[32:35] offset:36864
	ds_write_b128 v212, v[36:39] offset:36864
	ds_write_b128 v224, v[40:43] offset:36864
	ds_write_b128 v225, v[44:47] offset:36864
	v_mfma_f32_16x16x32_bf16 v[32:35], v[84:87], v[120:123], v[80:83]
	s_waitcnt lgkmcnt(0)
	s_barrier
; #define LAS __attribute__((address_space(3)))
; __device__ __forceinline__ f32x4 mfma16(bf16x8 a, bf16x8 b, f32x4 c) { return __builtin_amdgcn_mfma_f32_16x16x32_bf16(a, b, c, 0, 0, 0); }
; __device__ __forceinline__ bf16x8 pack8(f32x4 a, f32x4 b) { u32x4 w; w.x = pk2(a[0], a[1]); w.y = pk2(a[2], a[3]); w.z = pk2(b[0], b[1]); w.w = pk2(b[2], b[3]); return __builtin_bit_cast(bf16x8, w); }
; __device__ __forceinline__ void xattn_unit(const Args& a, LAS unsigned char* lds, int b, int h, int qb, int tid, int wave, int lane) {
;     ...
;     for (int j = 0; j < 8; ++j) {
;         if (j < 6) gload(j + 2);
;         const LAS bf16* base = (const LAS bf16*)(lds + (j & 1) * STG);
;         if (j < 4) {
; #pragma unroll
;             for (int rt = 0; rt < 4; ++rt)
; #pragma unroll
;                 for (int kk = 0; kk < 8; ++kk) S[4 * j + rt] = mfma16(*(const LAS bf16x8*)(base + (16 * rt + fr) * KS + 32 * kk + 8 * fq), qf[kk], S[4 * j + rt]);
;             if (j == 3) {
;                 float mx = -3.0e38f;
; #pragma unroll
;                 for (int i = 0; i < 16; ++i) mx = fmaxf(mx, fmaxf(fmaxf(S[i][0], S[i][1]), fmaxf(S[i][2], S[i][3])));
;                 mx = fmaxf(mx, __shfl_xor(mx, 16)); mx = fmaxf(mx, __shfl_xor(mx, 32));
; #pragma unroll
;                 for (int i = 0; i < 16; ++i)
; #pragma unroll
;                     for (int k = 0; k < 4; ++k) { S[i][k] = __builtin_amdgcn_exp2f(S[i][k] - mx); l += S[i][k]; }
;                 l += __shfl_xor(l, 16); l += __shfl_xor(l, 32);
; #pragma unroll
;                 for (int c2 = 0; c2 < 8; ++c2) pf[c2] = pack8(S[2 * c2], S[2 * c2 + 1]);
;             }
;         } else {
;             const int mt = j - 4;
; #pragma unroll
;             for (int dt = 0; dt < 16; ++dt) {
;                 const LAS bf16* vr = base + (16 * dt + fr) * VS + 4 * fq;
;                 O[dt] = mfma16(cat8(*(const LAS u32x2*)vr, *(const LAS u32x2*)(vr + 16)), pf[2 * mt], O[dt]);
;                 O[dt] = mfma16(cat8(*(const LAS u32x2*)(vr + 32), *(const LAS u32x2*)(vr + 48)), pf[2 * mt + 1], O[dt]);
;             }
;         }
;         if (j < 7) lstore(j + 1);
;         __syncthreads();
	ds_read_b128 v[44:47], v210 offset:36864
	ds_read_b128 v[80:83], v210 offset:36928
	v_mfma_f32_16x16x32_bf16 v[140:143], v[140:143], v[156:159], 0
	v_mfma_f32_16x16x32_bf16 v[36:39], v[128:131], v[120:123], v[124:127]
	ds_read_b128 v[84:87], v210 offset:45312
	s_nop 1
	ds_read_b128 v[124:127], v210 offset:45376
	s_waitcnt lgkmcnt(3)
	v_mfma_f32_16x16x32_bf16 v[44:47], v[44:47], v[156:159], 0
	v_mfma_f32_16x16x32_bf16 v[48:51], v[56:59], v[112:115], v[48:51]
	v_mfma_f32_16x16x32_bf16 v[40:43], v[164:167], v[120:123], v[140:143]
	ds_read_b128 v[128:131], v210 offset:53760
	s_nop 1
	ds_read_b128 v[140:143], v210 offset:53824
	ds_read_b128 v[164:167], v209 offset:36864
	ds_read_b128 v[188:191], v209 offset:36928
	s_waitcnt lgkmcnt(5)
	v_mfma_f32_16x16x32_bf16 v[84:87], v[84:87], v[156:159], 0
	v_mfma_f32_16x16x32_bf16 v[32:35], v[88:91], v[112:115], v[32:35]
	v_mfma_f32_16x16x32_bf16 v[44:47], v[80:83], v[120:123], v[44:47]
	v_mfma_f32_16x16x32_bf16 v[48:51], v[60:63], v[104:107], v[48:51]
	ds_read_b128 v[60:63], v210 offset:36992
	ds_read_b128 v[88:91], v210 offset:37056
	s_waitcnt lgkmcnt(5)
	v_mfma_f32_16x16x32_bf16 v[128:131], v[128:131], v[156:159], 0
	v_mfma_f32_16x16x32_bf16 v[56:59], v[124:127], v[120:123], v[84:87]
	v_mfma_f32_16x16x32_bf16 v[32:35], v[92:95], v[104:107], v[32:35]
	s_waitcnt lgkmcnt(1)
	v_mfma_f32_16x16x32_bf16 v[44:47], v[60:63], v[112:115], v[44:47]
	ds_read_b128 v[60:63], v210 offset:45440
	ds_read_b128 v[92:95], v210 offset:45504
	v_mfma_f32_16x16x32_bf16 v[164:167], v[164:167], v[156:159], 0
	v_mfma_f32_16x16x32_bf16 v[80:83], v[140:143], v[120:123], v[128:131]
	s_waitcnt lgkmcnt(1)
	v_mfma_f32_16x16x32_bf16 v[56:59], v[60:63], v[112:115], v[56:59]
	ds_read_b128 v[60:63], v210 offset:53888
	ds_read_b128 v[124:127], v210 offset:53952
	v_mfma_f32_16x16x32_bf16 v[84:87], v[188:191], v[120:123], v[164:167]
	s_waitcnt lgkmcnt(1)
	v_mfma_f32_16x16x32_bf16 v[60:63], v[60:63], v[112:115], v[80:83]
	s_nop 2
	ds_read_b128 v[80:83], v209 offset:36992
	ds_read_b128 v[128:131], v209 offset:37056
	v_mfma_f32_16x16x32_bf16 v[40:43], v[168:171], v[112:115], v[40:43]
	s_waitcnt lgkmcnt(1)
	v_mfma_f32_16x16x32_bf16 v[80:83], v[80:83], v[112:115], v[84:87]
	v_mfma_f32_16x16x32_bf16 v[48:51], v[64:67], v[28:31], v[48:51]
	v_mfma_f32_16x16x32_bf16 v[40:43], v[172:175], v[104:107], v[40:43]
	v_mfma_f32_16x16x32_bf16 v[44:47], v[88:91], v[104:107], v[44:47]
	s_waitcnt lgkmcnt(0)
	v_mfma_f32_16x16x32_bf16 v[64:67], v[128:131], v[104:107], v[80:83]
	v_mfma_f32_16x16x32_bf16 v[48:51], v[68:71], v[8:11], v[48:51]
	ds_read_b128 v[68:71], v210 offset:37120
	s_nop 0
	ds_read_b128 v[80:83], v210 offset:37184
	v_mfma_f32_16x16x32_bf16 v[32:35], v[96:99], v[28:31], v[32:35]
	v_mfma_f32_16x16x32_bf16 v[40:43], v[176:179], v[28:31], v[40:43]
	v_mfma_f32_16x16x32_bf16 v[56:59], v[92:95], v[104:107], v[56:59]
	s_waitcnt lgkmcnt(1)
	v_mfma_f32_16x16x32_bf16 v[44:47], v[68:71], v[28:31], v[44:47]
	ds_read_b128 v[68:71], v210 offset:45568
	ds_read_b128 v[84:87], v210 offset:45632
	v_mfma_f32_16x16x32_bf16 v[36:39], v[132:135], v[112:115], v[36:39]
	v_mfma_f32_16x16x32_bf16 v[60:63], v[124:127], v[104:107], v[60:63]
	v_mfma_f32_16x16x32_bf16 v[32:35], v[100:103], v[8:11], v[32:35]
	v_mfma_f32_16x16x32_bf16 v[40:43], v[180:183], v[8:11], v[40:43]
	s_waitcnt lgkmcnt(1)
	v_mfma_f32_16x16x32_bf16 v[56:59], v[68:71], v[28:31], v[56:59]
	ds_read_b128 v[68:71], v210 offset:54016
	ds_read_b128 v[88:91], v210 offset:54080
	v_mfma_f32_16x16x32_bf16 v[36:39], v[136:139], v[104:107], v[36:39]
	s_waitcnt lgkmcnt(1)
	v_mfma_f32_16x16x32_bf16 v[60:63], v[68:71], v[28:31], v[60:63]
	ds_read_b128 v[68:71], v209 offset:37120
	ds_read_b128 v[92:95], v209 offset:37184
	v_mfma_f32_16x16x32_bf16 v[48:51], v[72:75], v[4:7], v[48:51]
	v_mfma_f32_16x16x32_bf16 v[32:35], v[108:111], v[4:7], v[32:35]
	v_mfma_f32_16x16x32_bf16 v[52:55], v[52:55], v[4:7], v[40:43]
	v_mfma_f32_16x16x32_bf16 v[36:39], v[144:147], v[28:31], v[36:39]
	s_waitcnt lgkmcnt(1)
	v_mfma_f32_16x16x32_bf16 v[64:67], v[68:71], v[28:31], v[64:67]
	v_mfma_f32_16x16x32_bf16 v[68:71], v[80:83], v[8:11], v[44:47]
	v_mfma_f32_16x16x32_bf16 v[44:47], v[76:79], v[0:3], v[48:51]
	v_mfma_f32_16x16x32_bf16 v[40:43], v[116:119], v[0:3], v[32:35]
	v_mfma_f32_16x16x32_bf16 v[32:35], v[184:187], v[0:3], v[52:55]
	s_nop 0
	ds_read_b128 v[48:51], v210 offset:37248
	s_nop 0
	ds_read_b128 v[52:55], v210 offset:37312
	v_mfma_f32_16x16x32_bf16 v[36:39], v[148:151], v[8:11], v[36:39]
	v_mfma_f32_16x16x32_bf16 v[56:59], v[84:87], v[8:11], v[56:59]
	v_lshlrev_b32_e32 v84, 10, v200
	v_and_or_b32 v205, v84, s19, v219
	v_add_u32_e32 v206, 0x80000, v205
	s_waitcnt lgkmcnt(1)
	v_mfma_f32_16x16x32_bf16 v[48:51], v[48:51], v[4:7], v[68:71]
	s_nop 2
	ds_read_b128 v[68:71], v210 offset:45696
	ds_read_b128 v[72:75], v210 offset:45760
	v_add_u32_e32 v207, 0x100000, v205
	v_add_u32_e32 v208, 0x180000, v205
	v_mfma_f32_16x16x32_bf16 v[36:39], v[152:155], v[4:7], v[36:39]
	v_mfma_f32_16x16x32_bf16 v[60:63], v[88:91], v[8:11], v[60:63]
	s_waitcnt lgkmcnt(1)
	v_mfma_f32_16x16x32_bf16 v[56:59], v[68:71], v[4:7], v[56:59]
	ds_read_b128 v[68:71], v210 offset:54144
	ds_read_b128 v[76:79], v210 offset:54208
	v_mfma_f32_16x16x32_bf16 v[36:39], v[160:163], v[0:3], v[36:39]
	s_waitcnt lgkmcnt(1)
	v_mfma_f32_16x16x32_bf16 v[60:63], v[68:71], v[4:7], v[60:63]
	ds_read_b128 v[68:71], v209 offset:37248
	ds_read_b128 v[80:83], v209 offset:37312
	global_load_dwordx4 v[160:163], v193, s[8:9]
	global_load_dwordx4 v[164:167], v194, s[8:9]
	global_load_dwordx4 v[168:171], v195, s[8:9]
	global_load_dwordx4 v[172:175], v196, s[8:9]
	v_mfma_f32_16x16x32_bf16 v[64:67], v[92:95], v[8:11], v[64:67]
	s_waitcnt vmcnt(7)
	ds_write_b128 v211, v[12:15]
	s_waitcnt vmcnt(6)
	ds_write_b128 v212, v[16:19]
	s_waitcnt vmcnt(5)
	ds_write_b128 v224, v[20:23]
	s_waitcnt vmcnt(4)
	ds_write_b128 v225, v[24:27]
	s_waitcnt lgkmcnt(0)
	s_barrier
; __device__ __forceinline__ void xattn_unit(const Args& a, LAS unsigned char* lds, int b, int h, int qb, int tid, int wave, int lane) {
;     ...
;     const unsigned vok = (unsigned)((tid >> 5) * DM + 8 * (tid & 31)) * 2u, vov = (unsigned)((tid >> 3) * MEMR + 8 * (tid & 7)) * 2u;
;     const GAS char* kxb = (const GAS char*)KX + ((size_t)b * 256 * DM + h * 256) * 2; const GAS char* vxb = (const GAS char*)VTX + ((size_t)h * 256 * MEMR + b * 256) * 2;
;     auto gload = [&](int j) {
;         if (j < 4) { const GAS char* p_ = kxb + (size_t)j * (64 * DM * 2);
; #pragma unroll
;             for (int i = 0; i < 4; ++i) rr[j & 1][i] = *(const GAS u32x4*)(p_ + (size_t)(vok + (unsigned)(i * 16 * DM * 2)));
;         } else { const GAS char* p_ = vxb + (size_t)(j - 4) * 128;
; #pragma unroll
;             for (int i = 0; i < 4; ++i) rr[j & 1][i] = *(const GAS u32x4*)(p_ + (size_t)(vov + (unsigned)(i * 64 * MEMR * 2)));
;         }
;     };
;     auto lstore = [&](int j) {
;         LAS bf16* base = (LAS bf16*)(lds + (j & 1) * STG);
;         if (j < 4) {
; #pragma unroll
;             for (int i = 0; i < 4; ++i) { const int id = tid + 512 * i; *(LAS u32x4*)(base + (id >> 5) * KS + 8 * (id & 31)) = rr[j & 1][i]; }
;         } else {
; #pragma unroll
;             for (int i = 0; i < 4; ++i) { const int id = tid + 512 * i; *(LAS u32x4*)(base + (id >> 3) * VS + 8 * (id & 7)) = rr[j & 1][i]; }
;         }
;     };
;     f32x4 S[16]; bf16x8 pf[8]; f32x4 O[16]; float l = 0.f;
; #pragma unroll
;     for (int i = 0; i < 16; ++i) { S[i] = (f32x4){0.f, 0.f, 0.f, 0.f}; O[i] = (f32x4){0.f, 0.f, 0.f, 0.f}; }
;     gload(0); gload(1); lstore(0); __syncthreads();
; #pragma unroll
;     for (int j = 0; j < 8; ++j) {
;         if (j < 6) gload(j + 2);
;         const LAS bf16* base = (const LAS bf16*)(lds + (j & 1) * STG);
;         if (j < 4) {
; #pragma unroll
;             for (int rt = 0; rt < 4; ++rt)
; #pragma unroll
;                 for (int kk = 0; kk < 8; ++kk) S[4 * j + rt] = mfma16(*(const LAS bf16x8*)(base + (16 * rt + fr) * KS + 32 * kk + 8 * fq), qf[kk], S[4 * j + rt]);
;             if (j == 3) {
;                 float mx = -3.0e38f;
; #pragma unroll
;                 for (int i = 0; i < 16; ++i) mx = fmaxf(mx, fmaxf(fmaxf(S[i][0], S[i][1]), fmaxf(S[i][2], S[i][3])));
;                 mx = fmaxf(mx, __shfl_xor(mx, 16)); mx = fmaxf(mx, __shfl_xor(mx, 32));
; #pragma unroll
	v_mfma_f32_16x16x32_bf16 v[64:67], v[68:71], v[4:7], v[64:67]
	global_load_dwordx4 v[12:15], v205, s[6:7]
	global_load_dwordx4 v[16:19], v206, s[6:7]
	global_load_dwordx4 v[20:23], v207, s[6:7]
	global_load_dwordx4 v[24:27], v208, s[6:7]
	v_mfma_f32_16x16x32_bf16 v[52:55], v[52:55], v[0:3], v[48:51]
	v_mfma_f32_16x16x32_bf16 v[56:59], v[72:75], v[0:3], v[56:59]
	v_mfma_f32_16x16x32_bf16 v[60:63], v[76:79], v[0:3], v[60:63]
	v_mfma_f32_16x16x32_bf16 v[48:51], v[80:83], v[0:3], v[64:67]
	ds_read_b128 v[76:79], v210
	ds_read_b128 v[84:87], v210 offset:64
	ds_read_b128 v[220:223], v210 offset:128
	ds_read_b128 v[132:135], v210 offset:192
	ds_read_b128 v[124:127], v210 offset:256
	ds_read_b128 v[116:119], v210 offset:320
	ds_read_b128 v[72:75], v210 offset:384
	ds_read_b128 v[64:67], v210 offset:448
	ds_read_b128 v[88:91], v210 offset:8448
	ds_read_b128 v[176:179], v210 offset:8512
	ds_read_b128 v[228:231], v210 offset:8576
	ds_read_b128 v[140:143], v210 offset:8640
	ds_read_b128 v[128:131], v210 offset:8704
	ds_read_b128 v[108:111], v210 offset:8768
	ds_read_b128 v[80:83], v210 offset:8832
	ds_read_b128 v[68:71], v210 offset:8896
	ds_read_b128 v[92:95], v210 offset:16896
	ds_read_b128 v[180:183], v210 offset:16960
	ds_read_b128 v[232:235], v210 offset:17024
	ds_read_b128 v[148:151], v210 offset:17088
	ds_read_b128 v[96:99], v209
	s_waitcnt lgkmcnt(14)
	v_mfma_f32_16x16x32_bf16 v[184:187], v[76:79], v[156:159], 0
	s_waitcnt lgkmcnt(12)
	v_mfma_f32_16x16x32_bf16 v[188:191], v[88:91], v[156:159], 0
	ds_read_b128 v[136:139], v210 offset:17152
	ds_read_b128 v[100:103], v210 offset:17216
	ds_read_b128 v[88:91], v210 offset:17280
	ds_read_b128 v[76:79], v210 offset:17344
	ds_read_b128 v[196:199], v209 offset:64
	ds_read_b128 v[236:239], v209 offset:128
	s_waitcnt lgkmcnt(6)
	v_mfma_f32_16x16x32_bf16 v[240:243], v[96:99], v[156:159], 0
	ds_read_b128 v[152:155], v209 offset:192
	ds_read_b128 v[144:147], v209 offset:256
	ds_read_b128 v[96:99], v209 offset:320
	v_mfma_f32_16x16x32_bf16 v[192:195], v[92:95], v[156:159], 0
	v_mfma_f32_16x16x32_bf16 v[244:247], v[84:87], v[120:123], v[184:187]
	ds_read_b128 v[92:95], v209 offset:384
	ds_read_b128 v[84:87], v209 offset:448
	s_waitcnt vmcnt(7)
	ds_write_b128 v211, v[160:163] offset:36864
	s_waitcnt vmcnt(6)
	ds_write_b128 v212, v[164:167] offset:36864
	s_waitcnt vmcnt(5)
	ds_write_b128 v224, v[168:171] offset:36864
	s_waitcnt vmcnt(4)
	ds_write_b128 v225, v[172:175] offset:36864
	s_waitcnt lgkmcnt(0)
	s_barrier
	v_mfma_f32_16x16x32_bf16 v[172:175], v[196:199], v[120:123], v[240:243]
	ds_read_b128 v[164:167], v210 offset:36864
	s_nop 1
	ds_read_b128 v[240:243], v210 offset:36928
	v_cndmask_b32_e32 v211, v253, v227, vcc
	v_lshlrev_b32_e32 v211, 2, v211
	s_waitcnt lgkmcnt(1)
	v_mfma_f32_16x16x32_bf16 v[248:251], v[164:167], v[156:159], 0
	ds_read_b128 v[164:167], v210 offset:45312
	ds_read_b128 v[184:187], v210 offset:45376
	v_cmp_lt_i32_e32 vcc, v204, v226
	v_mfma_f32_16x16x32_bf16 v[160:163], v[176:179], v[120:123], v[188:191]
	s_nop 0
	v_cndmask_b32_e32 v212, v253, v204, vcc
	v_lshlrev_b32_e32 v212, 2, v212
	v_mfma_f32_16x16x32_bf16 v[168:171], v[180:183], v[120:123], v[192:195]
	s_waitcnt lgkmcnt(1)
	v_mfma_f32_16x16x32_bf16 v[188:191], v[164:167], v[156:159], 0
	ds_read_b128 v[164:167], v210 offset:53760
	ds_read_b128 v[192:195], v210 offset:53824
	s_waitcnt lgkmcnt(1)
	v_mfma_f32_16x16x32_bf16 v[196:199], v[164:167], v[156:159], 0
	ds_read_b128 v[164:167], v209 offset:36864
	ds_read_b128 v[176:179], v209 offset:36928
	s_waitcnt lgkmcnt(1)
	v_mfma_f32_16x16x32_bf16 v[180:183], v[164:167], v[156:159], 0
	v_mfma_f32_16x16x32_bf16 v[164:167], v[220:223], v[112:115], v[244:247]
	v_lshrrev_b32_e32 v220, 1, v200
	v_lshrrev_b32_e32 v221, 3, v200
	v_and_b32_e32 v200, 24, v220
	v_mfma_f32_16x16x32_bf16 v[160:163], v[228:231], v[112:115], v[160:163]
	v_or_b32_e32 v222, 0x70, v214
	v_or_b32_e32 v223, 0xf0, v214
	v_mul_lo_u32 v220, v221, s22
	v_mfma_f32_16x16x32_bf16 v[156:159], v[232:235], v[112:115], v[168:171]
	v_mfma_f32_16x16x32_bf16 v[168:171], v[236:239], v[112:115], v[172:175]
	v_mfma_f32_16x16x32_bf16 v[184:187], v[184:187], v[120:123], v[188:191]
	v_mfma_f32_16x16x32_bf16 v[188:191], v[192:195], v[120:123], v[196:199]
	v_lshrrev_b32_e32 v192, 3, v217
	v_lshrrev_b32_e32 v193, 3, v218
	v_mfma_f32_16x16x32_bf16 v[172:175], v[240:243], v[120:123], v[248:251]
	s_waitcnt lgkmcnt(0)
	v_mfma_f32_16x16x32_bf16 v[120:123], v[176:179], v[120:123], v[180:183]
	v_mul_lo_u32 v178, v193, s22
	v_or_b32_e32 v177, 0xb0, v214
	v_add3_u32 v176, 0, v220, v219
	v_mfma_f32_16x16x32_bf16 v[132:135], v[132:135], v[104:107], v[164:167]
	s_nop 2
	v_mul_lo_u32 v164, v216, s22
	v_mul_lo_u32 v165, v192, s22
	v_mfma_f32_16x16x32_bf16 v[140:143], v[140:143], v[104:107], v[160:163]
	s_nop 2
	v_add3_u32 v160, 0, v164, v219
	v_add3_u32 v161, 0, v165, v219
	v_mfma_f32_16x16x32_bf16 v[164:167], v[148:151], v[104:107], v[156:159]
	v_add3_u32 v148, 0, v178, v219
	v_add_u32_e32 v162, 0, v200
	v_mad_u32_u24 v151, v215, s22, v162
	v_mfma_f32_16x16x32_bf16 v[168:171], v[152:155], v[104:107], v[168:171]
	ds_read_b128 v[152:155], v210 offset:36992
	ds_read_b128 v[178:181], v210 offset:37056
	v_mad_u32_u24 v156, v213, s22, v162
	v_mad_u32_u24 v150, v177, s22, v162
	s_waitcnt lgkmcnt(1)
	v_mfma_f32_16x16x32_bf16 v[172:175], v[152:155], v[112:115], v[172:175]
	ds_read_b128 v[152:155], v210 offset:45440
	ds_read_b128 v[192:195], v210 offset:45504
	v_mad_u32_u24 v149, v223, s22, v162
	v_add_u32_e32 v158, 0x2000, v156
	s_waitcnt lgkmcnt(1)
; #define LAS __attribute__((address_space(3)))
; __device__ __forceinline__ f32x4 mfma16(bf16x8 a, bf16x8 b, f32x4 c) { return __builtin_amdgcn_mfma_f32_16x16x32_bf16(a, b, c, 0, 0, 0); }
; __device__ __forceinline__ bf16x8 pack8(f32x4 a, f32x4 b) { u32x4 w; w.x = pk2(a[0], a[1]); w.y = pk2(a[2], a[3]); w.z = pk2(b[0], b[1]); w.w = pk2(b[2], b[3]); return __builtin_bit_cast(bf16x8, w); }
; __device__ __forceinline__ void xattn_unit(const Args& a, LAS unsigned char* lds, int b, int h, int qb, int tid, int wave, int lane) {
;     ...
;         if (j < 4) {
; #pragma unroll
;             for (int rt = 0; rt < 4; ++rt)
; #pragma unroll
;                 for (int kk = 0; kk < 8; ++kk) S[4 * j + rt] = mfma16(*(const LAS bf16x8*)(base + (16 * rt + fr) * KS + 32 * kk + 8 * fq), qf[kk], S[4 * j + rt]);
;             if (j == 3) {
;                 float mx = -3.0e38f;
; #pragma unroll
;                 for (int i = 0; i < 16; ++i) mx = fmaxf(mx, fmaxf(fmaxf(S[i][0], S[i][1]), fmaxf(S[i][2], S[i][3])));
;                 mx = fmaxf(mx, __shfl_xor(mx, 16)); mx = fmaxf(mx, __shfl_xor(mx, 32));
; #pragma unroll
;                 for (int i = 0; i < 16; ++i)
; #pragma unroll
;                     for (int k = 0; k < 4; ++k) { S[i][k] = __builtin_amdgcn_exp2f(S[i][k] - mx); l += S[i][k]; }
;                 l += __shfl_xor(l, 16); l += __shfl_xor(l, 32);
; #pragma unroll
;                 for (int c2 = 0; c2 < 8; ++c2) pf[c2] = pack8(S[2 * c2], S[2 * c2 + 1]);
;             }
;         } else {
;             const int mt = j - 4;
; #pragma unroll
;             for (int dt = 0; dt < 16; ++dt) {
;                 const LAS bf16* vr = base + (16 * dt + fr) * VS + 4 * fq;
;                 O[dt] = mfma16(cat8(*(const LAS u32x2*)vr, *(const LAS u32x2*)(vr + 16)), pf[2 * mt], O[dt]);
;                 O[dt] = mfma16(cat8(*(const LAS u32x2*)(vr + 32), *(const LAS u32x2*)(vr + 48)), pf[2 * mt + 1], O[dt]);
;             }
;         }
;         if (j < 7) lstore(j + 1);
;         __syncthreads();
	v_mfma_f32_16x16x32_bf16 v[182:185], v[152:155], v[112:115], v[184:187]
	ds_read_b128 v[152:155], v210 offset:53888
	ds_read_b128 v[196:199], v210 offset:53952
	v_add_u32_e32 v159, 0x2800, v156
	v_add_u32_e32 v157, 0x3000, v156
	s_waitcnt lgkmcnt(1)
	v_mfma_f32_16x16x32_bf16 v[186:189], v[152:155], v[112:115], v[188:191]
	ds_read_b128 v[152:155], v209 offset:36992
	ds_read_b128 v[214:217], v209 offset:37056
	v_add_u32_e32 v163, 0x800, v156
	s_waitcnt lgkmcnt(1)
	v_mfma_f32_16x16x32_bf16 v[218:221], v[152:155], v[112:115], v[120:123]
	v_mad_u32_u24 v152, v222, s22, v162
	v_add_u32_e32 v162, 0x1000, v156
	v_add_u32_e32 v154, 0x4800, v156
	v_mfma_f32_16x16x32_bf16 v[228:231], v[124:127], v[28:31], v[132:135]
	v_add_u32_e32 v155, 0x5000, v156
	v_add_u32_e32 v153, 0x5800, v156
	v_mfma_f32_16x16x32_bf16 v[132:135], v[136:139], v[28:31], v[164:167]
	v_add_u32_e32 v139, 0x6800, v156
	v_lshl_add_u64 v[136:137], s[4:5], 0, v[202:203]
	v_add_u32_e32 v138, 0x9000, v156
	v_mfma_f32_16x16x32_bf16 v[112:115], v[144:147], v[28:31], v[168:171]
	v_add_u32_e32 v146, 0x7000, v156
	v_add_u32_e32 v144, 0x7800, v156
	v_add_u32_e32 v145, 0x9800, v156
	v_mfma_f32_16x16x32_bf16 v[140:143], v[128:131], v[28:31], v[140:143]
	v_add_u32_e32 v147, 0xa000, v156
	v_add_u32_e32 v164, 0x9000, v151
	v_add_u32_e32 v165, 0xb000, v156
	v_mfma_f32_16x16x32_bf16 v[120:123], v[178:181], v[104:107], v[172:175]
	v_add_u32_e32 v166, 0xb800, v156
	v_add_u32_e32 v167, 0xc000, v156
	v_add_u32_e32 v168, 0x9000, v152
	v_mfma_f32_16x16x32_bf16 v[100:103], v[100:103], v[8:11], v[132:135]
	v_add_u32_e32 v169, 0xd800, v156
	v_add_u32_e32 v170, 0xe000, v156
	v_add_u32_e32 v171, 0xe800, v156
	v_mfma_f32_16x16x32_bf16 v[96:99], v[96:99], v[8:11], v[112:115]
	s_nop 2
	ds_read_b128 v[112:115], v210 offset:37120
	ds_read_b128 v[132:135], v210 offset:37184
	v_add_u32_e32 v172, 0x9000, v150
	v_add_u32_e32 v173, 0xf800, v156
	v_mfma_f32_16x16x32_bf16 v[124:127], v[192:195], v[104:107], v[182:185]
	v_add_u32_e32 v177, 0x7000, v138
	v_add_u32_e32 v175, 0x7800, v138
	v_add_u32_e32 v174, 0x9000, v149
	v_mfma_f32_16x16x32_bf16 v[108:111], v[108:111], v[8:11], v[140:143]
	v_lshl_add_u64 v[136:137], v[136:137], 0, s[0:1]
	v_lshl_add_u64 v[136:137], v[136:137], 0, v[200:201]
	s_waitcnt lgkmcnt(1)
	v_mfma_f32_16x16x32_bf16 v[112:115], v[112:115], v[28:31], v[120:123]
	s_nop 2
	ds_read_b128 v[120:123], v210 offset:45568
	ds_read_b128 v[140:143], v210 offset:45632
	v_mfma_f32_16x16x32_bf16 v[128:131], v[196:199], v[104:107], v[186:189]
	s_waitcnt lgkmcnt(1)
	v_mfma_f32_16x16x32_bf16 v[120:123], v[120:123], v[28:31], v[124:127]
	s_nop 2
	ds_read_b128 v[124:127], v210 offset:54016
	ds_read_b128 v[178:181], v210 offset:54080
	v_mfma_f32_16x16x32_bf16 v[104:107], v[214:217], v[104:107], v[218:221]
	s_waitcnt lgkmcnt(1)
	v_mfma_f32_16x16x32_bf16 v[124:127], v[124:127], v[28:31], v[128:131]
	s_nop 2
	ds_read_b128 v[128:131], v209 offset:37120
	ds_read_b128 v[182:185], v209 offset:37184
	v_mfma_f32_16x16x32_bf16 v[116:119], v[116:119], v[8:11], v[228:231]
	s_waitcnt lgkmcnt(1)
	v_mfma_f32_16x16x32_bf16 v[28:31], v[128:131], v[28:31], v[104:107]
	s_nop 2
	v_max_f32_e32 v104, v47, v47
	v_max_f32_e32 v105, v46, v46
	v_max_f32_e32 v106, v43, v43
	v_max_f32_e32 v107, v42, v42
	v_mfma_f32_16x16x32_bf16 v[72:75], v[72:75], v[4:7], v[116:119]
	v_max_f32_e32 v104, v105, v104
	s_nop 1
	v_max_f32_e32 v116, v39, v39
	v_max_f32_e32 v117, v38, v38
	v_mfma_f32_16x16x32_bf16 v[80:83], v[80:83], v[4:7], v[108:111]
	s_nop 2
	v_max_f32_e32 v108, v35, v35
	v_max_f32_e32 v109, v34, v34
	v_mfma_f32_16x16x32_bf16 v[88:91], v[88:91], v[4:7], v[100:103]
	s_nop 2
	v_max_f32_e32 v100, v107, v106
	v_max_f32_e32 v101, v117, v116
	v_max_f32_e32 v102, v109, v108
	v_max3_f32 v103, v44, v45, v104
	v_max3_f32 v100, v40, v41, v100
	v_mfma_f32_16x16x32_bf16 v[92:95], v[92:95], v[4:7], v[96:99]
	v_max3_f32 v101, v36, v37, v101
	v_max3_f32 v102, v32, v33, v102
	v_max3_f32 v100, v103, s21, v100
	v_mfma_f32_16x16x32_bf16 v[96:99], v[132:135], v[8:11], v[112:115]
	v_max_f32_e32 v108, v55, v55
	v_max_f32_e32 v109, v54, v54
	v_max_f32_e32 v116, v62, v62
	v_max_f32_e32 v113, v59, v59
	v_max_f32_e32 v114, v58, v58
	v_max3_f32 v112, v100, v101, v102
	v_mfma_f32_16x16x32_bf16 v[100:103], v[140:143], v[8:11], v[120:123]
	v_max_f32_e32 v115, v63, v63
	v_mfma_f32_16x16x32_bf16 v[104:107], v[178:181], v[8:11], v[124:127]
	s_waitcnt lgkmcnt(0)
	v_mfma_f32_16x16x32_bf16 v[8:11], v[182:185], v[8:11], v[28:31]
	s_nop 2
	v_max_f32_e32 v28, v51, v51
	v_max_f32_e32 v29, v50, v50
	v_max_f32_e32 v30, v109, v108
	v_max_f32_e32 v31, v114, v113
	v_mfma_f32_16x16x32_bf16 v[108:111], v[64:67], v[0:3], v[72:75]
	v_max_f32_e32 v64, v116, v115
	v_max_f32_e32 v28, v29, v28
	v_max3_f32 v29, v52, v53, v30
	v_max3_f32 v30, v56, v57, v31
	v_max3_f32 v31, v60, v61, v64
	v_max3_f32 v28, v48, v49, v28
	v_max3_f32 v29, v112, v29, v30
	v_max3_f32 v116, v29, v31, v28
	ds_read_b128 v[28:31], v210 offset:37248
	ds_read_b128 v[72:75], v210 offset:37312
	v_mfma_f32_16x16x32_bf16 v[76:79], v[76:79], v[0:3], v[88:91]
	v_max_f32_e32 v117, v111, v111
	v_max_f32_e32 v118, v110, v110
	v_mfma_f32_16x16x32_bf16 v[84:87], v[84:87], v[0:3], v[92:95]
	s_waitcnt lgkmcnt(1)
	v_mfma_f32_16x16x32_bf16 v[88:91], v[28:31], v[4:7], v[96:99]
	ds_read_b128 v[28:31], v210 offset:45696
	ds_read_b128 v[92:95], v210 offset:45760
	s_waitcnt lgkmcnt(1)
	v_mfma_f32_16x16x32_bf16 v[96:99], v[28:31], v[4:7], v[100:103]
	ds_read_b128 v[28:31], v210 offset:54144
	s_nop 1
	ds_read_b128 v[100:103], v210 offset:54208
	s_waitcnt lgkmcnt(1)
	v_mfma_f32_16x16x32_bf16 v[104:107], v[28:31], v[4:7], v[104:107]
	ds_read_b128 v[28:31], v209 offset:37248
	ds_read_b128 v[112:115], v209 offset:37312
	v_mfma_f32_16x16x32_bf16 v[80:83], v[68:71], v[0:3], v[80:83]
	s_waitcnt lgkmcnt(1)
	v_mfma_f32_16x16x32_bf16 v[4:7], v[28:31], v[4:7], v[8:11]
	global_load_dwordx4 v[68:71], v205, s[6:7] offset:128
	global_load_dwordx4 v[28:31], v206, s[6:7] offset:128
	global_load_dwordx4 v[64:67], v207, s[6:7] offset:128
	v_mfma_f32_16x16x32_bf16 v[8:11], v[72:75], v[0:3], v[88:91]
	global_load_dwordx4 v[72:75], v208, s[6:7] offset:128
	s_waitcnt vmcnt(7)
	ds_write_b128 v176, v[12:15]
	s_waitcnt vmcnt(6)
	ds_write_b128 v160, v[16:19]
	s_waitcnt vmcnt(5)
	ds_write_b128 v161, v[20:23]
	s_waitcnt vmcnt(4)
	ds_write_b128 v148, v[24:27]
	s_waitcnt lgkmcnt(0)
	v_mfma_f32_16x16x32_bf16 v[88:91], v[92:95], v[0:3], v[96:99]
	s_barrier
; #define LAS __attribute__((address_space(3)))
; __device__ __forceinline__ f32x4 mfma16(bf16x8 a, bf16x8 b, f32x4 c) { return __builtin_amdgcn_mfma_f32_16x16x32_bf16(a, b, c, 0, 0, 0); }
; __device__ __forceinline__ bf16x8 pack8(f32x4 a, f32x4 b) { u32x4 w; w.x = pk2(a[0], a[1]); w.y = pk2(a[2], a[3]); w.z = pk2(b[0], b[1]); w.w = pk2(b[2], b[3]); return __builtin_bit_cast(bf16x8, w); }
; __device__ __forceinline__ void xattn_unit(const Args& a, LAS unsigned char* lds, int b, int h, int qb, int tid, int wave, int lane) {
;     ...
;             if (j == 3) {
;                 float mx = -3.0e38f;
; #pragma unroll
;                 for (int i = 0; i < 16; ++i) mx = fmaxf(mx, fmaxf(fmaxf(S[i][0], S[i][1]), fmaxf(S[i][2], S[i][3])));
;                 mx = fmaxf(mx, __shfl_xor(mx, 16)); mx = fmaxf(mx, __shfl_xor(mx, 32));
; #pragma unroll
;                 for (int i = 0; i < 16; ++i)
; #pragma unroll
;                     for (int k = 0; k < 4; ++k) { S[i][k] = __builtin_amdgcn_exp2f(S[i][k] - mx); l += S[i][k]; }
;                 l += __shfl_xor(l, 16); l += __shfl_xor(l, 32);
; #pragma unroll
;                 for (int c2 = 0; c2 < 8; ++c2) pf[c2] = pack8(S[2 * c2], S[2 * c2 + 1]);
;             }
;         } else {
;             const int mt = j - 4;
; #pragma unroll
;             for (int dt = 0; dt < 16; ++dt) {
;                 const LAS bf16* vr = base + (16 * dt + fr) * VS + 4 * fq;
;                 O[dt] = mfma16(cat8(*(const LAS u32x2*)vr, *(const LAS u32x2*)(vr + 16)), pf[2 * mt], O[dt]);
;                 O[dt] = mfma16(cat8(*(const LAS u32x2*)(vr + 32), *(const LAS u32x2*)(vr + 48)), pf[2 * mt + 1], O[dt]);
	ds_read2_b64 v[12:15], v156 offset1:4
	ds_read2_b64 v[16:19], v163 offset0:32 offset1:36
	v_max_f32_e32 v96, v83, v83
	v_max_f32_e32 v97, v82, v82
	v_max_f32_e32 v98, v79, v79
	v_mfma_f32_16x16x32_bf16 v[92:95], v[100:103], v[0:3], v[104:107]
	v_max_f32_e32 v99, v78, v78
	v_max_f32_e32 v100, v87, v87
	v_max_f32_e32 v101, v86, v86
	v_mfma_f32_16x16x32_bf16 v[0:3], v[112:115], v[0:3], v[4:7]
	ds_read2_b64 v[20:23], v162 offset0:64 offset1:68
	ds_read2_b64 v[24:27], v151 offset1:4
	ds_read2_b64 v[112:115], v156 offset0:8 offset1:12
	v_max_f32_e32 v4, v118, v117
	v_max_f32_e32 v5, v97, v96
	v_max_f32_e32 v6, v99, v98
	v_max_f32_e32 v7, v101, v100
	v_max3_f32 v4, v108, v109, v4
	v_max3_f32 v5, v80, v81, v5
	v_max3_f32 v6, v76, v77, v6
	v_max3_f32 v7, v84, v85, v7
	v_max3_f32 v4, v116, v4, v5
	v_max3_f32 v4, v4, v6, v7
	v_max_f32_e32 v5, v11, v11
	v_max_f32_e32 v6, v10, v10
	v_max_f32_e32 v7, v91, v91
	v_max_f32_e32 v96, v90, v90
	v_max_f32_e32 v97, v95, v95
	v_max_f32_e32 v98, v94, v94
	v_max_f32_e32 v99, v3, v3
	v_max_f32_e32 v100, v2, v2
	v_max_f32_e32 v5, v6, v5
	v_max_f32_e32 v6, v96, v7
	v_max_f32_e32 v7, v98, v97
	v_max_f32_e32 v96, v100, v99
	v_max3_f32 v5, v8, v9, v5
	v_max3_f32 v6, v88, v89, v6
	v_max3_f32 v7, v92, v93, v7
	v_max3_f32 v96, v0, v1, v96
	v_max3_f32 v4, v4, v5, v6
	v_max3_f32 v4, v4, v7, v96
	ds_bpermute_b32 v5, v211, v4
	s_waitcnt lgkmcnt(0)
	v_max_f32_e32 v5, v5, v5
	v_max_f32_e32 v4, v4, v5
	ds_bpermute_b32 v5, v212, v4
	s_waitcnt lgkmcnt(0)
	v_max_f32_e32 v5, v5, v5
	v_max_f32_e32 v4, v4, v5
	v_sub_f32_e32 v5, v44, v4
	v_sub_f32_e32 v6, v45, v4
	v_sub_f32_e32 v7, v46, v4
	v_sub_f32_e32 v44, v47, v4
	v_sub_f32_e32 v40, v40, v4
	v_sub_f32_e32 v41, v41, v4
	v_sub_f32_e32 v42, v42, v4
	v_sub_f32_e32 v43, v43, v4
	v_sub_f32_e32 v36, v36, v4
	v_sub_f32_e32 v37, v37, v4
	v_sub_f32_e32 v38, v38, v4
	v_sub_f32_e32 v39, v39, v4
	v_sub_f32_e32 v32, v32, v4
	v_sub_f32_e32 v33, v33, v4
	v_sub_f32_e32 v34, v34, v4
	v_sub_f32_e32 v35, v35, v4
	v_sub_f32_e32 v45, v52, v4
	v_sub_f32_e32 v46, v53, v4
	v_sub_f32_e32 v47, v54, v4
	v_sub_f32_e32 v52, v55, v4
	v_sub_f32_e32 v53, v56, v4
	v_sub_f32_e32 v54, v57, v4
	v_sub_f32_e32 v55, v58, v4
	v_sub_f32_e32 v56, v59, v4
	v_sub_f32_e32 v57, v60, v4
	v_sub_f32_e32 v58, v61, v4
	v_sub_f32_e32 v59, v62, v4
	v_sub_f32_e32 v60, v63, v4
	v_sub_f32_e32 v48, v48, v4
	v_sub_f32_e32 v49, v49, v4
	v_sub_f32_e32 v50, v50, v4
	v_sub_f32_e32 v51, v51, v4
	v_sub_f32_e32 v61, v108, v4
	v_sub_f32_e32 v62, v109, v4
	v_sub_f32_e32 v63, v110, v4
	v_sub_f32_e32 v96, v111, v4
	v_sub_f32_e32 v80, v80, v4
	v_sub_f32_e32 v81, v81, v4
	v_sub_f32_e32 v82, v82, v4
	v_sub_f32_e32 v83, v83, v4
	v_sub_f32_e32 v76, v76, v4
	v_sub_f32_e32 v77, v77, v4
	v_sub_f32_e32 v78, v78, v4
	v_sub_f32_e32 v79, v79, v4
	v_sub_f32_e32 v84, v84, v4
	v_sub_f32_e32 v85, v85, v4
	v_sub_f32_e32 v86, v86, v4
	v_sub_f32_e32 v87, v87, v4
	v_sub_f32_e32 v8, v8, v4
	v_sub_f32_e32 v9, v9, v4
	v_sub_f32_e32 v10, v10, v4
	v_sub_f32_e32 v11, v11, v4
	v_sub_f32_e32 v88, v88, v4
	v_sub_f32_e32 v89, v89, v4
	v_sub_f32_e32 v90, v90, v4
	v_sub_f32_e32 v91, v91, v4
	v_sub_f32_e32 v92, v92, v4
	v_sub_f32_e32 v93, v93, v4
	v_sub_f32_e32 v94, v94, v4
	v_sub_f32_e32 v95, v95, v4
	v_sub_f32_e32 v0, v0, v4
	v_sub_f32_e32 v1, v1, v4
	v_sub_f32_e32 v2, v2, v4
	v_sub_f32_e32 v3, v3, v4
	v_exp_f32_e32 v4, v5
	v_exp_f32_e32 v97, v6
	v_exp_f32_e32 v98, v7
	v_exp_f32_e32 v99, v44
	v_exp_f32_e32 v100, v40
	v_exp_f32_e32 v189, v52
	v_add_f32_e32 v52, 0, v4
	v_exp_f32_e32 v101, v41
	v_add_f32_e32 v52, v97, v52
	v_exp_f32_e32 v102, v42
	v_add_f32_e32 v52, v98, v52
	v_exp_f32_e32 v103, v43
	v_add_f32_e32 v52, v99, v52
	v_exp_f32_e32 v104, v36
	v_add_f32_e32 v52, v100, v52
	v_exp_f32_e32 v105, v37
	v_add_f32_e32 v52, v101, v52
	v_exp_f32_e32 v106, v38
	v_exp_f32_e32 v120, v39
	v_add_f32_e32 v52, v102, v52
	v_add_f32_e32 v52, v103, v52
	v_add_f32_e32 v52, v104, v52
	v_add_f32_e32 v52, v105, v52
	v_exp_f32_e32 v190, v53
	v_exp_f32_e32 v191, v54
	v_exp_f32_e32 v192, v55
	v_exp_f32_e32 v193, v56
	v_exp_f32_e32 v194, v57
	v_exp_f32_e32 v195, v58
	v_exp_f32_e32 v196, v59
	v_exp_f32_e32 v197, v60
	v_exp_f32_e32 v203, v61
	v_exp_f32_e32 v209, v62
	v_exp_f32_e32 v210, v63
	v_exp_f32_e32 v213, v96
	v_exp_f32_e32 v214, v80
	v_exp_f32_e32 v215, v81
	v_exp_f32_e32 v216, v82
	v_exp_f32_e32 v217, v83
	v_exp_f32_e32 v218, v76
	v_exp_f32_e32 v219, v77
	v_exp_f32_e32 v220, v78
	v_exp_f32_e32 v221, v79
	v_exp_f32_e32 v222, v84
	v_exp_f32_e32 v223, v85
	v_exp_f32_e32 v224, v86
	v_exp_f32_e32 v225, v87
	v_exp_f32_e32 v232, v88
	v_exp_f32_e32 v233, v89
	v_exp_f32_e32 v234, v90
	v_exp_f32_e32 v235, v91
	v_exp_f32_e32 v236, v92
	v_exp_f32_e32 v237, v93
	v_exp_f32_e32 v238, v94
	v_exp_f32_e32 v239, v95
	v_cvt_pk_bf16_f32 v36, v4, v97
	v_cvt_pk_bf16_f32 v37, v98, v99
	v_cvt_pk_bf16_f32 v38, v100, v101
	v_cvt_pk_bf16_f32 v39, v102, v103
	v_cvt_pk_bf16_f32 v40, v104, v105
	v_cvt_pk_bf16_f32 v41, v106, v120
	v_add_f32_e32 v121, v106, v52
	ds_read2_b64 v[52:55], v158 offset0:128 offset1:132
	ds_read2_b64 v[56:59], v159 offset0:160 offset1:164
	ds_read2_b64 v[60:63], v157 offset0:192 offset1:196
	ds_read2_b64 v[76:79], v152 offset1:4
	ds_read2_b64 v[80:83], v154 offset1:4
	ds_read2_b64 v[84:87], v155 offset0:32 offset1:36
	ds_read2_b64 v[88:91], v153 offset0:64 offset1:68
	ds_read2_b64 v[92:95], v150 offset1:4
	ds_read2_b64 v[96:99], v139 offset0:128 offset1:132
	ds_read2_b64 v[100:103], v146 offset0:160 offset1:164
	ds_read2_b64 v[104:107], v144 offset0:192 offset1:196
	ds_read2_b64 v[108:111], v149 offset1:4
	v_exp_f32_e32 v182, v32
	v_exp_f32_e32 v183, v33
	v_exp_f32_e32 v184, v34
	v_exp_f32_e32 v185, v35
	v_mfma_f32_16x16x32_bf16 v[12:15], v[12:15], v[36:39], 0
	v_cvt_pk_bf16_f32 v42, v182, v183
	v_add_f32_e32 v244, v120, v121
	v_cvt_pk_bf16_f32 v43, v184, v185
	v_mfma_f32_16x16x32_bf16 v[16:19], v[16:19], v[36:39], 0
	v_exp_f32_e32 v186, v45
	v_exp_f32_e32 v187, v46
	v_exp_f32_e32 v188, v47
	v_mfma_f32_16x16x32_bf16 v[20:23], v[20:23], v[36:39], 0
	v_cvt_pk_bf16_f32 v46, v190, v191
	v_cvt_pk_bf16_f32 v44, v186, v187
	v_cvt_pk_bf16_f32 v45, v188, v189
	v_mfma_f32_16x16x32_bf16 v[24:27], v[24:27], v[36:39], 0
	v_cvt_pk_bf16_f32 v47, v192, v193
	v_exp_f32_e32 v198, v48
	v_exp_f32_e32 v199, v49
	s_waitcnt lgkmcnt(11)
; #define LAS __attribute__((address_space(3)))
; __device__ __forceinline__ f32x4 mfma16(bf16x8 a, bf16x8 b, f32x4 c) { return __builtin_amdgcn_mfma_f32_16x16x32_bf16(a, b, c, 0, 0, 0); }
; __device__ __forceinline__ void xattn_unit(const Args& a, LAS unsigned char* lds, int b, int h, int qb, int tid, int wave, int lane) {
;     ...
;         } else {
;             const int mt = j - 4;
; #pragma unroll
;             for (int dt = 0; dt < 16; ++dt) {
;                 const LAS bf16* vr = base + (16 * dt + fr) * VS + 4 * fq;
;                 O[dt] = mfma16(cat8(*(const LAS u32x2*)vr, *(const LAS u32x2*)(vr + 16)), pf[2 * mt], O[dt]);
;                 O[dt] = mfma16(cat8(*(const LAS u32x2*)(vr + 32), *(const LAS u32x2*)(vr + 48)), pf[2 * mt + 1], O[dt]);
;             }
;         }
;         if (j < 7) lstore(j + 1);
;         __syncthreads();
	v_mfma_f32_16x16x32_bf16 v[52:55], v[52:55], v[36:39], 0
	v_exp_f32_e32 v200, v50
	v_exp_f32_e32 v202, v51
	v_cvt_pk_bf16_f32 v48, v194, v195
	s_waitcnt lgkmcnt(10)
	v_mfma_f32_16x16x32_bf16 v[56:59], v[56:59], v[36:39], 0
	v_cvt_pk_bf16_f32 v49, v196, v197
	v_cvt_pk_bf16_f32 v50, v198, v199
	v_cvt_pk_bf16_f32 v51, v200, v202
	s_waitcnt lgkmcnt(9)
	v_mfma_f32_16x16x32_bf16 v[60:63], v[60:63], v[36:39], 0
	v_add_f32_e32 v182, v182, v244
	v_exp_f32_e32 v228, v8
	v_exp_f32_e32 v229, v9
	s_waitcnt lgkmcnt(8)
	v_mfma_f32_16x16x32_bf16 v[76:79], v[76:79], v[36:39], 0
	v_exp_f32_e32 v230, v10
	v_exp_f32_e32 v231, v11
	v_exp_f32_e32 v240, v0
	s_waitcnt lgkmcnt(7)
	v_mfma_f32_16x16x32_bf16 v[80:83], v[80:83], v[36:39], 0
	v_exp_f32_e32 v241, v1
	v_exp_f32_e32 v242, v2
	v_exp_f32_e32 v243, v3
	s_waitcnt lgkmcnt(6)
	v_mfma_f32_16x16x32_bf16 v[84:87], v[84:87], v[36:39], 0
	v_cvt_pk_bf16_f32 v32, v203, v209
	v_cvt_pk_bf16_f32 v33, v210, v213
	v_cvt_pk_bf16_f32 v34, v214, v215
	s_waitcnt lgkmcnt(5)
	v_mfma_f32_16x16x32_bf16 v[88:91], v[88:91], v[36:39], 0
	v_cvt_pk_bf16_f32 v35, v216, v217
	v_cvt_pk_bf16_f32 v8, v218, v219
	v_cvt_pk_bf16_f32 v9, v220, v221
	s_waitcnt lgkmcnt(4)
	v_mfma_f32_16x16x32_bf16 v[92:95], v[92:95], v[36:39], 0
	v_cvt_pk_bf16_f32 v10, v222, v223
	v_cvt_pk_bf16_f32 v11, v224, v225
	v_cvt_pk_bf16_f32 v4, v228, v229
	s_waitcnt lgkmcnt(3)
	v_mfma_f32_16x16x32_bf16 v[96:99], v[96:99], v[36:39], 0
	v_cvt_pk_bf16_f32 v5, v230, v231
	v_cvt_pk_bf16_f32 v6, v232, v233
	v_cvt_pk_bf16_f32 v7, v234, v235
	s_waitcnt lgkmcnt(2)
	v_mfma_f32_16x16x32_bf16 v[100:103], v[100:103], v[36:39], 0
	v_cvt_pk_bf16_f32 v0, v236, v237
	v_cvt_pk_bf16_f32 v1, v238, v239
	v_cvt_pk_bf16_f32 v2, v240, v241
	s_waitcnt lgkmcnt(1)
	v_mfma_f32_16x16x32_bf16 v[104:107], v[104:107], v[36:39], 0
	v_cvt_pk_bf16_f32 v3, v242, v243
	s_waitcnt lgkmcnt(0)
	v_mfma_f32_16x16x32_bf16 v[36:39], v[108:111], v[36:39], 0
	ds_read2_b64 v[108:111], v163 offset0:40 offset1:44
	v_mfma_f32_16x16x32_bf16 v[12:15], v[112:115], v[40:43], v[12:15]
	ds_read2_b64 v[112:115], v162 offset0:72 offset1:76
	s_waitcnt lgkmcnt(1)
	v_mfma_f32_16x16x32_bf16 v[16:19], v[108:111], v[40:43], v[16:19]
	ds_read2_b64 v[108:111], v151 offset0:8 offset1:12
	s_waitcnt lgkmcnt(1)
	v_mfma_f32_16x16x32_bf16 v[20:23], v[112:115], v[40:43], v[20:23]
	ds_read2_b64 v[112:115], v158 offset0:136 offset1:140
	s_waitcnt lgkmcnt(1)
	v_mfma_f32_16x16x32_bf16 v[24:27], v[108:111], v[40:43], v[24:27]
	ds_read2_b64 v[108:111], v159 offset0:168 offset1:172
	s_waitcnt lgkmcnt(1)
	v_mfma_f32_16x16x32_bf16 v[52:55], v[112:115], v[40:43], v[52:55]
	ds_read2_b64 v[112:115], v157 offset0:200 offset1:204
	s_waitcnt lgkmcnt(1)
	v_mfma_f32_16x16x32_bf16 v[56:59], v[108:111], v[40:43], v[56:59]
	ds_read2_b64 v[108:111], v152 offset0:8 offset1:12
	s_waitcnt lgkmcnt(1)
	v_mfma_f32_16x16x32_bf16 v[60:63], v[112:115], v[40:43], v[60:63]
	ds_read2_b64 v[112:115], v154 offset0:8 offset1:12
	ds_read2_b64 v[116:119], v155 offset0:40 offset1:44
	ds_read2_b64 v[120:123], v153 offset0:72 offset1:76
	s_waitcnt lgkmcnt(3)
	v_mfma_f32_16x16x32_bf16 v[76:79], v[108:111], v[40:43], v[76:79]
	global_load_dwordx4 v[108:111], v205, s[6:7] offset:256
	s_waitcnt lgkmcnt(2)
	v_mfma_f32_16x16x32_bf16 v[80:83], v[112:115], v[40:43], v[80:83]
	global_load_dwordx4 v[112:115], v206, s[6:7] offset:256
	global_load_dwordx4 v[124:127], v207, s[6:7] offset:256
	ds_read2_b64 v[128:131], v150 offset0:8 offset1:12
	s_waitcnt lgkmcnt(2)
	v_mfma_f32_16x16x32_bf16 v[84:87], v[116:119], v[40:43], v[84:87]
	global_load_dwordx4 v[116:119], v208, s[6:7] offset:256
	ds_read2_b64 v[132:135], v139 offset0:136 offset1:140
	ds_read2_b64 v[140:143], v146 offset0:168 offset1:172
	s_waitcnt lgkmcnt(3)
	v_mfma_f32_16x16x32_bf16 v[88:91], v[120:123], v[40:43], v[88:91]
	ds_read2_b64 v[120:123], v144 offset0:200 offset1:204
	ds_read2_b64 v[178:181], v149 offset0:8 offset1:12
	s_waitcnt vmcnt(7)
	ds_write_b128 v176, v[68:71] offset:36864
	s_waitcnt vmcnt(6)
	ds_write_b128 v160, v[28:31] offset:36864
	s_waitcnt vmcnt(5)
	ds_write_b128 v161, v[64:67] offset:36864
	s_waitcnt vmcnt(4)
	ds_write_b128 v148, v[72:75] offset:36864
	s_waitcnt lgkmcnt(0)
	s_barrier
	ds_read2_b64 v[72:75], v138 offset1:4
	v_mfma_f32_16x16x32_bf16 v[92:95], v[128:131], v[40:43], v[92:95]
	v_add_f32_e32 v128, v183, v182
	v_add_f32_e32 v128, v184, v128
	v_mfma_f32_16x16x32_bf16 v[68:71], v[132:135], v[40:43], v[96:99]
	v_mfma_f32_16x16x32_bf16 v[28:31], v[140:143], v[40:43], v[100:103]
	v_mfma_f32_16x16x32_bf16 v[64:67], v[120:123], v[40:43], v[104:107]
	v_mfma_f32_16x16x32_bf16 v[36:39], v[178:181], v[40:43], v[36:39]
	ds_read2_b64 v[40:43], v145 offset0:32 offset1:36
	v_add_f32_e32 v178, v185, v128
	v_add_f32_e32 v178, v186, v178
	s_waitcnt lgkmcnt(1)
	v_mfma_f32_16x16x32_bf16 v[12:15], v[72:75], v[44:47], v[12:15]
	ds_read2_b64 v[72:75], v147 offset0:64 offset1:68
	v_add_f32_e32 v178, v187, v178
	s_waitcnt lgkmcnt(1)
	v_mfma_f32_16x16x32_bf16 v[16:19], v[40:43], v[44:47], v[16:19]
	ds_read2_b64 v[40:43], v164 offset1:4
	s_waitcnt lgkmcnt(1)
	v_mfma_f32_16x16x32_bf16 v[20:23], v[72:75], v[44:47], v[20:23]
	ds_read2_b64 v[72:75], v165 offset0:128 offset1:132
	s_waitcnt lgkmcnt(1)
	v_mfma_f32_16x16x32_bf16 v[24:27], v[40:43], v[44:47], v[24:27]
	ds_read2_b64 v[40:43], v166 offset0:160 offset1:164
	s_waitcnt lgkmcnt(1)
	v_mfma_f32_16x16x32_bf16 v[52:55], v[72:75], v[44:47], v[52:55]
	ds_read2_b64 v[72:75], v167 offset0:192 offset1:196
	s_waitcnt lgkmcnt(1)
	v_mfma_f32_16x16x32_bf16 v[40:43], v[40:43], v[44:47], v[56:59]
	s_nop 2
	ds_read2_b64 v[56:59], v168 offset1:4
	s_waitcnt lgkmcnt(1)
; #define LAS __attribute__((address_space(3)))
; __device__ __forceinline__ f32x4 mfma16(bf16x8 a, bf16x8 b, f32x4 c) { return __builtin_amdgcn_mfma_f32_16x16x32_bf16(a, b, c, 0, 0, 0); }
; __device__ __forceinline__ void xattn_unit(const Args& a, LAS unsigned char* lds, int b, int h, int qb, int tid, int wave, int lane) {
;     ...
;         } else {
;             const int mt = j - 4;
; #pragma unroll
;             for (int dt = 0; dt < 16; ++dt) {
;                 const LAS bf16* vr = base + (16 * dt + fr) * VS + 4 * fq;
;                 O[dt] = mfma16(cat8(*(const LAS u32x2*)vr, *(const LAS u32x2*)(vr + 16)), pf[2 * mt], O[dt]);
;                 O[dt] = mfma16(cat8(*(const LAS u32x2*)(vr + 32), *(const LAS u32x2*)(vr + 48)), pf[2 * mt + 1], O[dt]);
;             }
;         }
;         if (j < 7) lstore(j + 1);
;         __syncthreads();
	v_mfma_f32_16x16x32_bf16 v[60:63], v[72:75], v[44:47], v[60:63]
	ds_read2_b64 v[72:75], v169 offset1:4
	s_waitcnt lgkmcnt(1)
	v_mfma_f32_16x16x32_bf16 v[56:59], v[56:59], v[44:47], v[76:79]
	s_nop 2
	ds_read2_b64 v[76:79], v170 offset0:32 offset1:36
	s_waitcnt lgkmcnt(1)
	v_mfma_f32_16x16x32_bf16 v[72:75], v[72:75], v[44:47], v[80:83]
	s_nop 2
	ds_read2_b64 v[80:83], v171 offset0:64 offset1:68
	s_waitcnt lgkmcnt(1)
	v_mfma_f32_16x16x32_bf16 v[76:79], v[76:79], v[44:47], v[84:87]
	s_nop 2
	ds_read2_b64 v[84:87], v172 offset1:4
	s_waitcnt lgkmcnt(1)
	v_mfma_f32_16x16x32_bf16 v[80:83], v[80:83], v[44:47], v[88:91]
	s_nop 2
	ds_read2_b64 v[88:91], v173 offset0:128 offset1:132
	s_waitcnt lgkmcnt(1)
	v_mfma_f32_16x16x32_bf16 v[84:87], v[84:87], v[44:47], v[92:95]
	s_nop 2
	ds_read2_b64 v[92:95], v177 offset0:160 offset1:164
	s_waitcnt lgkmcnt(1)
	v_mfma_f32_16x16x32_bf16 v[68:71], v[88:91], v[44:47], v[68:71]
	ds_read2_b64 v[88:91], v175 offset0:192 offset1:196
	s_waitcnt lgkmcnt(1)
	v_mfma_f32_16x16x32_bf16 v[28:31], v[92:95], v[44:47], v[28:31]
	ds_read2_b64 v[92:95], v174 offset1:4
	s_waitcnt lgkmcnt(1)
	v_mfma_f32_16x16x32_bf16 v[64:67], v[88:91], v[44:47], v[64:67]
	ds_read2_b64 v[88:91], v138 offset0:8 offset1:12
	s_waitcnt lgkmcnt(1)
	v_mfma_f32_16x16x32_bf16 v[36:39], v[92:95], v[44:47], v[36:39]
	ds_read2_b64 v[44:47], v145 offset0:40 offset1:44
	s_waitcnt lgkmcnt(1)
	v_mfma_f32_16x16x32_bf16 v[12:15], v[88:91], v[48:51], v[12:15]
	ds_read2_b64 v[88:91], v147 offset0:72 offset1:76
	s_waitcnt lgkmcnt(1)
	v_mfma_f32_16x16x32_bf16 v[16:19], v[44:47], v[48:51], v[16:19]
	ds_read2_b64 v[44:47], v164 offset0:8 offset1:12
	s_waitcnt lgkmcnt(1)
	v_mfma_f32_16x16x32_bf16 v[20:23], v[88:91], v[48:51], v[20:23]
	ds_read2_b64 v[88:91], v165 offset0:136 offset1:140
	s_waitcnt lgkmcnt(1)
	v_mfma_f32_16x16x32_bf16 v[24:27], v[44:47], v[48:51], v[24:27]
	ds_read2_b64 v[44:47], v166 offset0:168 offset1:172
	s_waitcnt lgkmcnt(1)
	v_mfma_f32_16x16x32_bf16 v[52:55], v[88:91], v[48:51], v[52:55]
	ds_read2_b64 v[88:91], v167 offset0:200 offset1:204
	ds_read2_b64 v[92:95], v168 offset0:8 offset1:12
	ds_read2_b64 v[96:99], v169 offset0:8 offset1:12
	s_waitcnt lgkmcnt(3)
	v_mfma_f32_16x16x32_bf16 v[40:43], v[44:47], v[48:51], v[40:43]
	global_load_dwordx4 v[44:47], v205, s[6:7] offset:384
	s_waitcnt lgkmcnt(2)
	v_mfma_f32_16x16x32_bf16 v[60:63], v[88:91], v[48:51], v[60:63]
	global_load_dwordx4 v[88:91], v206, s[6:7] offset:384
	global_load_dwordx4 v[100:103], v207, s[6:7] offset:384
	ds_read2_b64 v[104:107], v170 offset0:40 offset1:44
	s_waitcnt lgkmcnt(2)
	v_mfma_f32_16x16x32_bf16 v[56:59], v[92:95], v[48:51], v[56:59]
	global_load_dwordx4 v[92:95], v208, s[6:7] offset:384
	ds_read2_b64 v[120:123], v171 offset0:72 offset1:76
	ds_read2_b64 v[128:131], v172 offset0:8 offset1:12
	s_waitcnt lgkmcnt(1)
	v_mfma_f32_16x16x32_bf16 v[80:83], v[120:123], v[48:51], v[80:83]
	v_add_f32_e32 v120, v188, v178
	v_add_f32_e32 v120, v189, v120
	v_add_f32_e32 v120, v190, v120
	v_mfma_f32_16x16x32_bf16 v[72:75], v[96:99], v[48:51], v[72:75]
	ds_read2_b64 v[96:99], v173 offset0:136 offset1:140
	ds_read2_b64 v[132:135], v177 offset0:168 offset1:172
	ds_read2_b64 v[140:143], v175 offset0:200 offset1:204
	v_add_f32_e32 v120, v191, v120
	v_add_f32_e32 v120, v192, v120
	v_add_f32_e32 v120, v193, v120
	v_mfma_f32_16x16x32_bf16 v[76:79], v[104:107], v[48:51], v[76:79]
	ds_read2_b64 v[104:107], v174 offset0:8 offset1:12
	s_waitcnt vmcnt(7)
	ds_write_b128 v176, v[108:111]
	s_waitcnt vmcnt(6)
	ds_write_b128 v160, v[112:115]
	s_waitcnt vmcnt(5)
	ds_write_b128 v161, v[124:127]
	s_waitcnt vmcnt(4)
	ds_write_b128 v148, v[116:119]
	s_waitcnt lgkmcnt(0)
	v_mfma_f32_16x16x32_bf16 v[68:71], v[96:99], v[48:51], v[68:71]
	v_add_f32_e32 v96, v194, v120
	v_add_f32_e32 v96, v195, v96
	v_add_f32_e32 v96, v196, v96
	v_add_f32_e32 v96, v197, v96
	v_add_f32_e32 v96, v198, v96
	v_add_f32_e32 v96, v199, v96
	v_add_f32_e32 v96, v200, v96
	v_add_f32_e32 v96, v202, v96
	v_add_f32_e32 v96, v203, v96
	v_mfma_f32_16x16x32_bf16 v[84:87], v[128:131], v[48:51], v[84:87]
	s_barrier
	v_mfma_f32_16x16x32_bf16 v[28:31], v[132:135], v[48:51], v[28:31]
	v_mfma_f32_16x16x32_bf16 v[64:67], v[140:143], v[48:51], v[64:67]
	v_mfma_f32_16x16x32_bf16 v[36:39], v[104:107], v[48:51], v[36:39]
	v_add_f32_e32 v48, v209, v96
	v_add_f32_e32 v48, v210, v48
	v_add_f32_e32 v48, v213, v48
	v_add_f32_e32 v48, v214, v48
	v_add_f32_e32 v48, v215, v48
	v_add_f32_e32 v48, v216, v48
	v_add_f32_e32 v48, v217, v48
	v_add_f32_e32 v48, v218, v48
	v_add_f32_e32 v48, v219, v48
	v_add_f32_e32 v48, v220, v48
	v_add_f32_e32 v48, v221, v48
	v_add_f32_e32 v48, v222, v48
	v_add_f32_e32 v48, v223, v48
	v_add_f32_e32 v48, v224, v48
	v_add_f32_e32 v48, v225, v48
	v_add_f32_e32 v48, v228, v48
	v_add_f32_e32 v48, v229, v48
	v_add_f32_e32 v48, v230, v48
	v_add_f32_e32 v48, v231, v48
	v_add_f32_e32 v48, v232, v48
	v_add_f32_e32 v48, v233, v48
	v_add_f32_e32 v48, v234, v48
	v_add_f32_e32 v48, v235, v48
	v_add_f32_e32 v48, v236, v48
	v_add_f32_e32 v48, v237, v48
	v_add_f32_e32 v48, v238, v48
	v_add_f32_e32 v48, v239, v48
	v_add_f32_e32 v48, v240, v48
	v_add_f32_e32 v48, v241, v48
	v_add_f32_e32 v48, v242, v48
	v_add_f32_e32 v48, v243, v48
	ds_bpermute_b32 v49, v211, v48
	s_waitcnt lgkmcnt(0)
	v_add_f32_e32 v48, v48, v49
	ds_bpermute_b32 v49, v212, v48
	s_waitcnt lgkmcnt(0)
; #define LAS __attribute__((address_space(3)))
; __device__ __forceinline__ f32x4 mfma16(bf16x8 a, bf16x8 b, f32x4 c) { return __builtin_amdgcn_mfma_f32_16x16x32_bf16(a, b, c, 0, 0, 0); }
; __device__ __forceinline__ void xattn_unit(const Args& a, LAS unsigned char* lds, int b, int h, int qb, int tid, int wave, int lane) {
;     ...
; #pragma unroll
;             for (int dt = 0; dt < 16; ++dt) {
;                 const LAS bf16* vr = base + (16 * dt + fr) * VS + 4 * fq;
;                 O[dt] = mfma16(cat8(*(const LAS u32x2*)vr, *(const LAS u32x2*)(vr + 16)), pf[2 * mt], O[dt]);
;                 O[dt] = mfma16(cat8(*(const LAS u32x2*)(vr + 32), *(const LAS u32x2*)(vr + 48)), pf[2 * mt + 1], O[dt]);
;             }
;         }
;         if (j < 7) lstore(j + 1);
;         __syncthreads();
;     }
;     const float il = 1.f / l;
	v_add_f32_e32 v48, v48, v49
	v_div_scale_f32 v49, s[6:7], v48, v48, 1.0
	v_rcp_f32_e32 v51, v49
	v_div_scale_f32 v50, vcc, 1.0, v48, 1.0
	v_fma_f32 v96, -v49, v51, 1.0
	v_fmac_f32_e32 v51, v96, v51
	v_mul_f32_e32 v96, v50, v51
	v_fma_f32 v97, -v49, v96, v50
	v_fmac_f32_e32 v96, v97, v51
	v_fma_f32 v49, -v49, v96, v50
	v_div_fmas_f32 v49, v49, v51, v96
	v_div_fixup_f32 v120, v49, v48, 1.0
	ds_read2_b64 v[108:111], v156 offset1:4
	ds_read2_b64 v[112:115], v163 offset0:32 offset1:36
	ds_read2_b64 v[116:119], v162 offset0:64 offset1:68
	ds_read2_b64 v[122:125], v151 offset1:4
	ds_read2_b64 v[126:129], v158 offset0:128 offset1:132
	ds_read2_b64 v[178:181], v159 offset0:160 offset1:164
	ds_read2_b64 v[182:185], v157 offset0:192 offset1:196
	ds_read2_b64 v[186:189], v152 offset1:4
	s_nop 0
	s_nop 0
	s_waitcnt lgkmcnt(7)
	v_mfma_f32_16x16x32_bf16 v[12:15], v[108:111], v[32:35], v[12:15]
	ds_read2_b64 v[190:193], v154 offset1:4
	s_nop 0
	s_waitcnt lgkmcnt(7)
	v_mfma_f32_16x16x32_bf16 v[16:19], v[112:115], v[32:35], v[16:19]
	ds_read2_b64 v[108:111], v155 offset0:32 offset1:36
	s_nop 0
	s_waitcnt lgkmcnt(7)
	v_mfma_f32_16x16x32_bf16 v[20:23], v[116:119], v[32:35], v[20:23]
	ds_read2_b64 v[112:115], v153 offset0:64 offset1:68
	s_nop 0
	s_waitcnt lgkmcnt(7)
	v_mfma_f32_16x16x32_bf16 v[24:27], v[122:125], v[32:35], v[24:27]
	ds_read2_b64 v[116:119], v150 offset1:4
	s_nop 0
	s_waitcnt lgkmcnt(7)
	v_mfma_f32_16x16x32_bf16 v[48:51], v[126:129], v[32:35], v[52:55]
	ds_read2_b64 v[122:125], v139 offset0:128 offset1:132
	s_nop 2
	s_nop 0
	s_waitcnt lgkmcnt(7)
	v_mfma_f32_16x16x32_bf16 v[40:43], v[178:181], v[32:35], v[40:43]
	ds_read2_b64 v[126:129], v146 offset0:160 offset1:164
	s_nop 0
	s_waitcnt lgkmcnt(7)
	v_mfma_f32_16x16x32_bf16 v[52:55], v[182:185], v[32:35], v[60:63]
	ds_read2_b64 v[178:181], v144 offset0:192 offset1:196
	s_nop 2
	s_nop 0
	s_waitcnt lgkmcnt(7)
	v_mfma_f32_16x16x32_bf16 v[56:59], v[186:189], v[32:35], v[56:59]
	ds_read2_b64 v[182:185], v149 offset1:4
	s_nop 0
	s_waitcnt lgkmcnt(7)
	v_mfma_f32_16x16x32_bf16 v[60:63], v[190:193], v[32:35], v[72:75]
	ds_read2_b64 v[186:189], v156 offset0:8 offset1:12
	s_nop 2
	s_nop 0
	s_waitcnt lgkmcnt(7)
	v_mfma_f32_16x16x32_bf16 v[76:79], v[108:111], v[32:35], v[76:79]
	ds_read2_b64 v[190:193], v163 offset0:40 offset1:44
	s_nop 0
	s_waitcnt lgkmcnt(7)
	v_mfma_f32_16x16x32_bf16 v[72:75], v[112:115], v[32:35], v[80:83]
	ds_read2_b64 v[108:111], v162 offset0:72 offset1:76
	s_nop 2
	s_nop 0
	s_waitcnt lgkmcnt(7)
	v_mfma_f32_16x16x32_bf16 v[84:87], v[116:119], v[32:35], v[84:87]
	ds_read2_b64 v[112:115], v151 offset0:8 offset1:12
	s_nop 0
	s_waitcnt lgkmcnt(7)
	v_mfma_f32_16x16x32_bf16 v[68:71], v[122:125], v[32:35], v[68:71]
	ds_read2_b64 v[116:119], v158 offset0:136 offset1:140
	s_nop 0
	s_waitcnt lgkmcnt(7)
	v_mfma_f32_16x16x32_bf16 v[28:31], v[126:129], v[32:35], v[28:31]
	ds_read2_b64 v[122:125], v159 offset0:168 offset1:172
	s_nop 0
	s_waitcnt lgkmcnt(7)
	v_mfma_f32_16x16x32_bf16 v[64:67], v[178:181], v[32:35], v[64:67]
	ds_read2_b64 v[126:129], v157 offset0:200 offset1:204
	s_nop 0
	s_waitcnt lgkmcnt(7)
	v_mfma_f32_16x16x32_bf16 v[32:35], v[182:185], v[32:35], v[36:39]
	ds_read2_b64 v[178:181], v152 offset0:8 offset1:12
	s_nop 2
	s_nop 0
	s_waitcnt lgkmcnt(7)
	v_mfma_f32_16x16x32_bf16 v[12:15], v[186:189], v[8:11], v[12:15]
	ds_read2_b64 v[182:185], v154 offset0:8 offset1:12
	s_nop 0
	s_waitcnt lgkmcnt(7)
	v_mfma_f32_16x16x32_bf16 v[16:19], v[190:193], v[8:11], v[16:19]
	ds_read2_b64 v[186:189], v155 offset0:40 offset1:44
	s_nop 0
	s_waitcnt lgkmcnt(7)
	v_mfma_f32_16x16x32_bf16 v[20:23], v[108:111], v[8:11], v[20:23]
	ds_read2_b64 v[190:193], v153 offset0:72 offset1:76
	s_nop 0
	s_waitcnt lgkmcnt(7)
	v_mfma_f32_16x16x32_bf16 v[24:27], v[112:115], v[8:11], v[24:27]
	ds_read2_b64 v[108:111], v150 offset0:8 offset1:12
	s_nop 0
	s_waitcnt lgkmcnt(7)
	v_mfma_f32_16x16x32_bf16 v[48:51], v[116:119], v[8:11], v[48:51]
	ds_read2_b64 v[112:115], v139 offset0:136 offset1:140
	s_nop 0
	s_waitcnt lgkmcnt(7)
	v_mfma_f32_16x16x32_bf16 v[36:39], v[122:125], v[8:11], v[40:43]
	s_nop 2
	s_nop 0
	s_waitcnt lgkmcnt(6)
	v_mfma_f32_16x16x32_bf16 v[52:55], v[126:129], v[8:11], v[52:55]
	s_nop 0
	s_waitcnt lgkmcnt(5)
	v_mfma_f32_16x16x32_bf16 v[40:43], v[178:181], v[8:11], v[56:59]
	s_nop 2
	s_nop 0
	s_waitcnt lgkmcnt(4)
	v_mfma_f32_16x16x32_bf16 v[60:63], v[182:185], v[8:11], v[60:63]
	s_nop 0
	s_waitcnt lgkmcnt(3)
	v_mfma_f32_16x16x32_bf16 v[56:59], v[186:189], v[8:11], v[76:79]
	s_nop 2
	s_nop 0
	s_waitcnt lgkmcnt(2)
	v_mfma_f32_16x16x32_bf16 v[72:75], v[190:193], v[8:11], v[72:75]
	s_nop 0
	ds_read2_b64 v[96:99], v146 offset0:168 offset1:172
	s_waitcnt lgkmcnt(2)
	v_mfma_f32_16x16x32_bf16 v[76:79], v[108:111], v[8:11], v[84:87]
	s_nop 2
	ds_read2_b64 v[84:87], v144 offset0:200 offset1:204
	ds_read2_b64 v[104:107], v149 offset0:8 offset1:12
	s_waitcnt vmcnt(3)
	ds_write_b128 v176, v[44:47] offset:36864
	s_waitcnt vmcnt(2)
	ds_write_b128 v160, v[88:91] offset:36864
	s_waitcnt vmcnt(1)
	ds_write_b128 v161, v[100:103] offset:36864
	s_waitcnt vmcnt(0)
	ds_write_b128 v148, v[92:95] offset:36864
	s_waitcnt lgkmcnt(7)
	v_mfma_f32_16x16x32_bf16 v[44:47], v[112:115], v[8:11], v[68:71]
	s_waitcnt lgkmcnt(0)
	s_barrier
; #define LAS __attribute__((address_space(3)))
; __device__ __forceinline__ unsigned pk2(float lo, float hi) { f32x2_t v = {lo, hi}; bf16x2_t b = __builtin_convertvector(v, bf16x2_t); return __builtin_bit_cast(unsigned, b); }
; __device__ __forceinline__ f32x4 mfma16(bf16x8 a, bf16x8 b, f32x4 c) { return __builtin_amdgcn_mfma_f32_16x16x32_bf16(a, b, c, 0, 0, 0); }
; __device__ __forceinline__ void xattn_unit(const Args& a, LAS unsigned char* lds, int b, int h, int qb, int tid, int wave, int lane) {
;     ...
; #pragma unroll
;             for (int dt = 0; dt < 16; ++dt) {
;                 const LAS bf16* vr = base + (16 * dt + fr) * VS + 4 * fq;
;                 O[dt] = mfma16(cat8(*(const LAS u32x2*)vr, *(const LAS u32x2*)(vr + 16)), pf[2 * mt], O[dt]);
;                 O[dt] = mfma16(cat8(*(const LAS u32x2*)(vr + 32), *(const LAS u32x2*)(vr + 48)), pf[2 * mt + 1], O[dt]);
;             }
;         }
;         if (j < 7) lstore(j + 1);
;         __syncthreads();
;     }
;     const float il = 1.f / l;
; #pragma unroll
;     for (int dt = 0; dt < 16; ++dt) { u32x2 w; w.x = pk2(O[dt][0] * il, O[dt][1] * il); w.y = pk2(O[dt][2] * il, O[dt][3] * il);
	v_mfma_f32_16x16x32_bf16 v[28:31], v[96:99], v[8:11], v[28:31]
	ds_read2_b64 v[108:111], v138 offset1:4
	ds_read2_b64 v[112:115], v145 offset0:32 offset1:36
	ds_read2_b64 v[116:119], v147 offset0:64 offset1:68
	ds_read2_b64 v[122:125], v164 offset1:4
	ds_read2_b64 v[126:129], v165 offset0:128 offset1:132
	ds_read2_b64 v[178:181], v166 offset0:160 offset1:164
	ds_read2_b64 v[182:185], v167 offset0:192 offset1:196
	ds_read2_b64 v[186:189], v168 offset1:4
	s_nop 0
	v_mfma_f32_16x16x32_bf16 v[64:67], v[84:87], v[8:11], v[64:67]
	v_mfma_f32_16x16x32_bf16 v[8:11], v[104:107], v[8:11], v[32:35]
	s_nop 2
	s_nop 0
	s_waitcnt lgkmcnt(7)
	v_mfma_f32_16x16x32_bf16 v[12:15], v[108:111], v[4:7], v[12:15]
	ds_read2_b64 v[190:193], v169 offset1:4
	s_nop 0
	s_waitcnt lgkmcnt(7)
	v_mfma_f32_16x16x32_bf16 v[16:19], v[112:115], v[4:7], v[16:19]
	ds_read2_b64 v[108:111], v170 offset0:32 offset1:36
	s_nop 0
	s_waitcnt lgkmcnt(7)
	v_mfma_f32_16x16x32_bf16 v[20:23], v[116:119], v[4:7], v[20:23]
	ds_read2_b64 v[112:115], v171 offset0:64 offset1:68
	s_nop 0
	s_waitcnt lgkmcnt(7)
	v_mfma_f32_16x16x32_bf16 v[24:27], v[122:125], v[4:7], v[24:27]
	ds_read2_b64 v[116:119], v172 offset1:4
	s_nop 0
	s_waitcnt lgkmcnt(7)
	v_mfma_f32_16x16x32_bf16 v[48:51], v[126:129], v[4:7], v[48:51]
	ds_read2_b64 v[122:125], v173 offset0:128 offset1:132
	s_nop 0
	s_waitcnt lgkmcnt(7)
	v_mfma_f32_16x16x32_bf16 v[32:35], v[178:181], v[4:7], v[36:39]
	ds_read2_b64 v[126:129], v177 offset0:160 offset1:164
	s_nop 2
	s_nop 0
	s_waitcnt lgkmcnt(7)
	v_mfma_f32_16x16x32_bf16 v[52:55], v[182:185], v[4:7], v[52:55]
	ds_read2_b64 v[178:181], v175 offset0:192 offset1:196
	s_nop 0
	s_waitcnt lgkmcnt(7)
	v_mfma_f32_16x16x32_bf16 v[36:39], v[186:189], v[4:7], v[40:43]
	ds_read2_b64 v[182:185], v174 offset1:4
	s_nop 2
	s_nop 0
	s_waitcnt lgkmcnt(7)
	v_mfma_f32_16x16x32_bf16 v[60:63], v[190:193], v[4:7], v[60:63]
	ds_read2_b64 v[186:189], v138 offset0:8 offset1:12
	s_nop 0
	s_waitcnt lgkmcnt(7)
	v_mfma_f32_16x16x32_bf16 v[40:43], v[108:111], v[4:7], v[56:59]
	ds_read2_b64 v[190:193], v145 offset0:40 offset1:44
	s_nop 2
	s_nop 0
	s_waitcnt lgkmcnt(7)
	v_mfma_f32_16x16x32_bf16 v[68:71], v[112:115], v[4:7], v[72:75]
	ds_read2_b64 v[108:111], v147 offset0:72 offset1:76
	s_nop 2
	s_nop 0
	s_waitcnt lgkmcnt(7)
	v_mfma_f32_16x16x32_bf16 v[56:59], v[116:119], v[4:7], v[76:79]
	ds_read2_b64 v[112:115], v164 offset0:8 offset1:12
	s_nop 2
	s_nop 0
	s_waitcnt lgkmcnt(7)
	v_mfma_f32_16x16x32_bf16 v[44:47], v[122:125], v[4:7], v[44:47]
	ds_read2_b64 v[116:119], v165 offset0:136 offset1:140
	s_nop 0
	s_waitcnt lgkmcnt(7)
	v_mfma_f32_16x16x32_bf16 v[28:31], v[126:129], v[4:7], v[28:31]
	ds_read2_b64 v[122:125], v166 offset0:168 offset1:172
	s_nop 0
	s_waitcnt lgkmcnt(7)
	v_mfma_f32_16x16x32_bf16 v[64:67], v[178:181], v[4:7], v[64:67]
	ds_read2_b64 v[126:129], v167 offset0:200 offset1:204
	s_nop 0
	s_waitcnt lgkmcnt(7)
	v_mfma_f32_16x16x32_bf16 v[4:7], v[182:185], v[4:7], v[8:11]
	ds_read2_b64 v[178:181], v168 offset0:8 offset1:12
	s_nop 2
	s_nop 0
	s_waitcnt lgkmcnt(7)
	v_mfma_f32_16x16x32_bf16 v[12:15], v[186:189], v[0:3], v[12:15]
	ds_read2_b64 v[182:185], v169 offset0:8 offset1:12
	s_nop 0
	s_waitcnt lgkmcnt(7)
	v_mfma_f32_16x16x32_bf16 v[8:11], v[190:193], v[0:3], v[16:19]
	ds_read2_b64 v[186:189], v170 offset0:40 offset1:44
	s_nop 2
	s_nop 0
	s_waitcnt lgkmcnt(7)
	v_mfma_f32_16x16x32_bf16 v[20:23], v[108:111], v[0:3], v[20:23]
	ds_read2_b64 v[190:193], v171 offset0:72 offset1:76
	s_nop 0
	s_nop 0
	v_pk_mul_f32 v[8:9], v[120:121], v[8:9] op_sel_hi:[0,1]
	v_pk_mul_f32 v[10:11], v[120:121], v[10:11] op_sel_hi:[0,1]
	s_waitcnt lgkmcnt(7)
	v_mfma_f32_16x16x32_bf16 v[16:19], v[112:115], v[0:3], v[24:27]
	ds_read2_b64 v[108:111], v172 offset0:8 offset1:12
	s_nop 2
	s_nop 0
	s_waitcnt lgkmcnt(7)
	v_mfma_f32_16x16x32_bf16 v[48:51], v[116:119], v[0:3], v[48:51]
	ds_read2_b64 v[112:115], v173 offset0:136 offset1:140
	s_nop 0
	s_nop 0
	v_pk_mul_f32 v[16:17], v[120:121], v[16:17] op_sel_hi:[0,1]
	v_pk_mul_f32 v[18:19], v[120:121], v[18:19] op_sel_hi:[0,1]
	s_waitcnt lgkmcnt(7)
	v_mfma_f32_16x16x32_bf16 v[24:27], v[122:125], v[0:3], v[32:35]
	ds_read2_b64 v[116:119], v177 offset0:168 offset1:172
	s_nop 2
	s_nop 0
	s_waitcnt lgkmcnt(7)
	v_mfma_f32_16x16x32_bf16 v[52:55], v[126:129], v[0:3], v[52:55]
	ds_read2_b64 v[122:125], v175 offset0:200 offset1:204
	s_nop 0
	s_nop 0
	v_pk_mul_f32 v[24:25], v[120:121], v[24:25] op_sel_hi:[0,1]
	v_pk_mul_f32 v[26:27], v[120:121], v[26:27] op_sel_hi:[0,1]
	s_waitcnt lgkmcnt(7)
	v_mfma_f32_16x16x32_bf16 v[32:35], v[178:181], v[0:3], v[36:39]
	ds_read2_b64 v[126:129], v174 offset0:8 offset1:12
	s_nop 2
	s_nop 0
	s_waitcnt lgkmcnt(7)
; #define LAS __attribute__((address_space(3)))
; #define GAS __attribute__((address_space(1)))
; __device__ __forceinline__ unsigned pk2(float lo, float hi) { f32x2_t v = {lo, hi}; bf16x2_t b = __builtin_convertvector(v, bf16x2_t); return __builtin_bit_cast(unsigned, b); }
; __device__ __forceinline__ f32x4 mfma16(bf16x8 a, bf16x8 b, f32x4 c) { return __builtin_amdgcn_mfma_f32_16x16x32_bf16(a, b, c, 0, 0, 0); }
; __device__ __forceinline__ void xattn_unit(const Args& a, LAS unsigned char* lds, int b, int h, int qb, int tid, int wave, int lane) {
;     ...
; #pragma unroll
;             for (int dt = 0; dt < 16; ++dt) {
;                 const LAS bf16* vr = base + (16 * dt + fr) * VS + 4 * fq;
;                 O[dt] = mfma16(cat8(*(const LAS u32x2*)vr, *(const LAS u32x2*)(vr + 16)), pf[2 * mt], O[dt]);
;                 O[dt] = mfma16(cat8(*(const LAS u32x2*)(vr + 32), *(const LAS u32x2*)(vr + 48)), pf[2 * mt + 1], O[dt]);
;             }
;         }
;         if (j < 7) lstore(j + 1);
;         __syncthreads();
;     }
;     const float il = 1.f / l;
; #pragma unroll
;     for (int dt = 0; dt < 16; ++dt) { u32x2 w; w.x = pk2(O[dt][0] * il, O[dt][1] * il); w.y = pk2(O[dt][2] * il, O[dt][3] * il);
;         *(GAS u32x2*)(XO + qrow * DM + h * 256 + 16 * dt + 4 * fq) = w; }
	v_mfma_f32_16x16x32_bf16 v[60:63], v[182:185], v[0:3], v[60:63]
	s_nop 0
	s_nop 0
	v_pk_mul_f32 v[32:33], v[120:121], v[32:33] op_sel_hi:[0,1]
	v_pk_mul_f32 v[34:35], v[120:121], v[34:35] op_sel_hi:[0,1]
	s_waitcnt lgkmcnt(6)
	v_mfma_f32_16x16x32_bf16 v[36:39], v[186:189], v[0:3], v[40:43]
	s_nop 2
	s_nop 0
	s_waitcnt lgkmcnt(5)
	v_mfma_f32_16x16x32_bf16 v[68:71], v[190:193], v[0:3], v[68:71]
	s_nop 0
	s_nop 0
	v_pk_mul_f32 v[36:37], v[120:121], v[36:37] op_sel_hi:[0,1]
	v_pk_mul_f32 v[38:39], v[120:121], v[38:39] op_sel_hi:[0,1]
	s_waitcnt lgkmcnt(4)
	v_mfma_f32_16x16x32_bf16 v[40:43], v[108:111], v[0:3], v[56:59]
	s_nop 2
	s_nop 0
	s_waitcnt lgkmcnt(3)
	v_mfma_f32_16x16x32_bf16 v[44:47], v[112:115], v[0:3], v[44:47]
	s_nop 0
	s_nop 0
	v_pk_mul_f32 v[40:41], v[120:121], v[40:41] op_sel_hi:[0,1]
	v_pk_mul_f32 v[42:43], v[120:121], v[42:43] op_sel_hi:[0,1]
	s_waitcnt lgkmcnt(2)
	v_mfma_f32_16x16x32_bf16 v[28:31], v[116:119], v[0:3], v[28:31]
	s_nop 0
	s_nop 0
	v_pk_mul_f32 v[44:45], v[120:121], v[44:45] op_sel_hi:[0,1]
	v_pk_mul_f32 v[46:47], v[120:121], v[46:47] op_sel_hi:[0,1]
	s_waitcnt lgkmcnt(1)
	v_mfma_f32_16x16x32_bf16 v[64:67], v[122:125], v[0:3], v[64:67]
	s_nop 1
	v_mul_f32_e64 v28, v120, v28
	v_mul_f32_e64 v29, v120, v29
	v_pk_mul_f32 v[30:31], v[120:121], v[30:31] op_sel_hi:[0,1]
	s_waitcnt lgkmcnt(0)
	v_mfma_f32_16x16x32_bf16 v[0:3], v[126:129], v[0:3], v[4:7]
	v_mul_f32_e64 v56, v120, v68
	v_mul_f32_e64 v57, v120, v69
	s_nop 0
	v_pk_mul_f32 v[4:5], v[120:121], v[12:13] op_sel_hi:[0,1]
	v_pk_mul_f32 v[6:7], v[120:121], v[14:15] op_sel_hi:[0,1]
	v_pk_mul_f32 v[12:13], v[120:121], v[20:21] op_sel_hi:[0,1]
	v_pk_mul_f32 v[14:15], v[120:121], v[22:23] op_sel_hi:[0,1]
	v_pk_mul_f32 v[20:21], v[120:121], v[48:49] op_sel_hi:[0,1]
	v_pk_mul_f32 v[22:23], v[120:121], v[50:51] op_sel_hi:[0,1]
	v_pk_mul_f32 v[48:49], v[120:121], v[52:53] op_sel_hi:[0,1]
	v_pk_mul_f32 v[50:51], v[120:121], v[54:55] op_sel_hi:[0,1]
	v_pk_mul_f32 v[52:53], v[120:121], v[60:61] op_sel_hi:[0,1]
	v_pk_mul_f32 v[54:55], v[120:121], v[62:63] op_sel_hi:[0,1]
	v_pk_mul_f32 v[58:59], v[120:121], v[70:71] op_sel_hi:[0,1]
	v_pk_mul_f32 v[60:61], v[120:121], v[64:65] op_sel_hi:[0,1]
	v_pk_mul_f32 v[62:63], v[120:121], v[66:67] op_sel_hi:[0,1]
	v_pk_mul_f32 v[0:1], v[120:121], v[0:1] op_sel_hi:[0,1]
	v_pk_mul_f32 v[2:3], v[120:121], v[2:3] op_sel_hi:[0,1]
	v_cvt_pk_bf16_f32 v4, v4, v5
	v_cvt_pk_bf16_f32 v5, v6, v7
	s_waitcnt lgkmcnt(0)
	s_barrier
	v_cvt_pk_bf16_f32 v6, v8, v9
	v_cvt_pk_bf16_f32 v7, v10, v11
	v_cvt_pk_bf16_f32 v8, v12, v13
	v_cvt_pk_bf16_f32 v9, v14, v15
	v_cvt_pk_bf16_f32 v10, v16, v17
	v_cvt_pk_bf16_f32 v11, v18, v19
	v_cvt_pk_bf16_f32 v12, v20, v21
	v_cvt_pk_bf16_f32 v13, v22, v23
	v_cvt_pk_bf16_f32 v14, v24, v25
	v_cvt_pk_bf16_f32 v15, v26, v27
	v_cvt_pk_bf16_f32 v16, v48, v49
	v_cvt_pk_bf16_f32 v17, v50, v51
	v_cvt_pk_bf16_f32 v18, v32, v33
	v_cvt_pk_bf16_f32 v19, v34, v35
	v_cvt_pk_bf16_f32 v20, v52, v53
	v_cvt_pk_bf16_f32 v21, v54, v55
	v_cvt_pk_bf16_f32 v22, v36, v37
	v_cvt_pk_bf16_f32 v23, v38, v39
	v_cvt_pk_bf16_f32 v24, v56, v57
	v_cvt_pk_bf16_f32 v25, v58, v59
	v_cvt_pk_bf16_f32 v26, v40, v41
	v_cvt_pk_bf16_f32 v27, v42, v43
	v_cvt_pk_bf16_f32 v36, v44, v45
	v_cvt_pk_bf16_f32 v37, v46, v47
	v_cvt_pk_bf16_f32 v38, v28, v29
	v_cvt_pk_bf16_f32 v39, v30, v31
	v_cvt_pk_bf16_f32 v40, v60, v61
	v_cvt_pk_bf16_f32 v41, v62, v63
	v_cvt_pk_bf16_f32 v42, v0, v1
	v_cvt_pk_bf16_f32 v43, v2, v3
	v_bfe_u32 v44, v252, 4, 1
	v_mul_u32_u24_e32 v44, 24, v44
	v_mov_b32_e32 v45, 0
	v_lshl_add_u64 v[44:45], v[136:137], 0, v[44:45]
	v_permlane16_swap_b32_e32 v4, v6
	v_permlane16_swap_b32_e32 v5, v7
	v_permlane16_swap_b32_e32 v8, v10
	v_permlane16_swap_b32_e32 v9, v11
	v_permlane16_swap_b32_e32 v12, v14
	v_permlane16_swap_b32_e32 v13, v15
	v_permlane16_swap_b32_e32 v16, v18
	v_permlane16_swap_b32_e32 v17, v19
	v_permlane16_swap_b32_e32 v20, v22
	v_permlane16_swap_b32_e32 v21, v23
	v_permlane16_swap_b32_e32 v24, v26
	v_permlane16_swap_b32_e32 v25, v27
	v_permlane16_swap_b32_e32 v36, v38
	v_permlane16_swap_b32_e32 v37, v39
	v_permlane16_swap_b32_e32 v40, v42
	v_permlane16_swap_b32_e32 v41, v43
	global_store_dwordx4 v[44:45], v[4:7], off
	global_store_dwordx4 v[44:45], v[8:11], off offset:64
	global_store_dwordx4 v[44:45], v[12:15], off offset:128
	global_store_dwordx4 v[44:45], v[16:19], off offset:192
	global_store_dwordx4 v[44:45], v[20:23], off offset:256
	global_store_dwordx4 v[44:45], v[24:27], off offset:320
	global_store_dwordx4 v[44:45], v[36:39], off offset:384
	global_store_dwordx4 v[44:45], v[40:43], off offset:448
	s_cbranch_scc0 .LBB0_1518
